# K-loop heads: the iteration's first 8-12 ds_reads are issued before the 7 loop-carried pointer-select SALU instructions (only the following DMA address needs them); all 5 GEMM loops
# speedup vs baseline: 1.0146x; 1.0020x over previous
; #define PG8_STAGE(bufoff, gbase, voff) do { _Pragma("unroll") for (int _i = 0; _i < 2; ++_i) \
;         __builtin_amdgcn_global_load_lds((const unsigned*)((const char*)(gbase) + (voff)[_i]), (PG8_LAS unsigned*)(lds + (bufoff) + ldsw + _i * 8192), 16, 0, 0); } while (0)
; #define PG8_LDA(dst, b, h) do { _Pragma("unroll") for (int m = 0; m < 4; ++m) _Pragma("unroll") for (int k = 0; k < 2; ++k) dst[m][k] = *(const PG8_LAS bf16x8*)(lds + PG8_SA(b, h) + aoff + m * 2048 + k * 1024); } while (0)
; #define PG8_LDB(dst, b, h) do { _Pragma("unroll") for (int n = 0; n < 2; ++n) _Pragma("unroll") for (int k = 0; k < 2; ++k) dst[n][k] = *(const PG8_LAS bf16x8*)(lds + PG8_SB(b, h) + boff + n * 2048 + k * 1024); } while (0)
; #define PG8_MMA(ai, bj, At, Bt) do { __builtin_amdgcn_s_setprio(1); _Pragma("unroll") for (int m = 0; m < 4; ++m) _Pragma("unroll") for (int n = 0; n < 2; ++n) _Pragma("unroll") for (int k = 0; k < 2; ++k) \
;         acc[ai][bj][m][n] = __builtin_amdgcn_mfma_f32_16x16x32_bf16(Bt[n][k], At[m][k], acc[ai][bj][m][n], 0, 0, 0); __builtin_amdgcn_s_setprio(0); } while (0)
; #define PG8_WAIT_V(n) asm volatile("s_waitcnt vmcnt(" #n ")" ::: "memory")
; #define PG8_WAIT_L(n) asm volatile("s_waitcnt lgkmcnt(" #n ")" ::: "memory")
; #define PG8_BAR __builtin_amdgcn_s_barrier()
; #define PG8_SCHED __builtin_amdgcn_sched_barrier(0)
; template <class Epi, class Sched, bool ALIGN_EPI = false, bool SP2 = false>
; __device__ __forceinline__ void gemm_phase(PG8_LAS unsigned char* lds, const Gemm g, const Sched& S, const Epi& E, int wave_s) {
;     ...
;             PG8_LDB(B0, 0, 0); PG8_LDB(B1, 0, 1); PG8_SCHED; PG8_LDA(At, 0, 0); PG8_STAGE(PG8_SA(1, 1), a1 + hstepA, voffA);
;             PG8_WAIT_V(8); PG8_WAIT_L(0); PG8_BAR; PG8_MMA(0, 0, At, B0); PG8_MMA(0, 1, At, B1); PG8_BAR; PG8_SCHED;
;             PG8_LDA(At, 0, 1); PG8_STAGE(PG8_SB(0, 0), b2, voffB); PG8_STAGE(PG8_SB(0, 1), b2 + hstepB, voffB); PG8_STAGE(PG8_SA(0, 0), a2, voffA);
;             PG8_WAIT_V(8); PG8_WAIT_L(0); PG8_BAR; PG8_MMA(1, 0, At, B0); PG8_MMA(1, 1, At, B1); PG8_BAR; PG8_SCHED;
.LBB0_314:
	s_add_i32 s85, 0, 0x10000
	s_add_i32 s89, 0, 0x14000
	v_add_u32_e32 v118, s85, v229
	v_add_u32_e32 v150, s89, v229
	ds_read_b128 v[106:109], v118
	ds_read_b128 v[110:113], v118 offset:1024
	ds_read_b128 v[114:117], v118 offset:2048
	ds_read_b128 v[118:121], v118 offset:3072
	ds_read_b128 v[122:125], v150
	ds_read_b128 v[126:129], v150 offset:1024
	ds_read_b128 v[142:145], v150 offset:2048
	ds_read_b128 v[150:153], v150 offset:3072
	s_add_u32 s30, s4, 0xfff80080
	s_addc_u32 s31, s5, -1
	s_cmp_eq_u32 s84, 4
	s_cselect_b32 s41, s91, s31
	s_cselect_b32 s40, s90, s30
	s_cselect_b32 s31, s2, s81
	s_cselect_b32 s30, s3, s29
	v_lshl_add_u64 v[194:195], s[4:5], 0, v[218:219]
	s_add_i32 m0, s35, 0xc000
	ds_read_b128 v[162:165], v230
	ds_read_b128 v[166:169], v230 offset:1024
	ds_read_b128 v[170:173], v230 offset:2048
	ds_read_b128 v[174:177], v230 offset:3072
	ds_read_b128 v[178:181], v230 offset:4096
	ds_read_b128 v[182:185], v230 offset:5120
	ds_read_b128 v[186:189], v230 offset:6144
	ds_read_b128 v[190:193], v230 offset:7168
	global_load_lds_dwordx4 v[194:195], off
	v_lshl_add_u64 v[194:195], s[4:5], 0, v[220:221]
	s_add_i32 m0, s35, 0xe000
	s_nop 0
	global_load_lds_dwordx4 v[194:195], off
	s_waitcnt vmcnt(8)
	s_waitcnt lgkmcnt(0)
	s_barrier
	s_waitcnt lgkmcnt(0)
	v_mfma_f32_16x16x32_bf16 v[158:161], v[106:109], v[162:165], v[158:161]
	v_mfma_f32_16x16x32_bf16 v[154:157], v[114:117], v[162:165], v[154:157]
	v_mfma_f32_16x16x32_bf16 v[134:137], v[106:109], v[170:173], v[134:137]
	v_mfma_f32_16x16x32_bf16 v[130:133], v[114:117], v[170:173], v[130:133]
	v_mfma_f32_16x16x32_bf16 v[94:97], v[106:109], v[178:181], v[94:97]
	v_mfma_f32_16x16x32_bf16 v[90:93], v[114:117], v[178:181], v[90:93]
	v_mfma_f32_16x16x32_bf16 v[78:81], v[106:109], v[186:189], v[78:81]
	v_mfma_f32_16x16x32_bf16 v[74:77], v[114:117], v[186:189], v[74:77]
	v_mfma_f32_16x16x32_bf16 v[158:161], v[110:113], v[166:169], v[158:161]
	v_mfma_f32_16x16x32_bf16 v[154:157], v[118:121], v[166:169], v[154:157]
	v_mfma_f32_16x16x32_bf16 v[134:137], v[110:113], v[174:177], v[134:137]
	v_mfma_f32_16x16x32_bf16 v[130:133], v[118:121], v[174:177], v[130:133]
	v_mfma_f32_16x16x32_bf16 v[94:97], v[110:113], v[182:185], v[94:97]
	v_mfma_f32_16x16x32_bf16 v[90:93], v[118:121], v[182:185], v[90:93]
	v_mfma_f32_16x16x32_bf16 v[78:81], v[110:113], v[190:193], v[78:81]
	v_mfma_f32_16x16x32_bf16 v[74:77], v[118:121], v[190:193], v[74:77]
	v_mfma_f32_16x16x32_bf16 v[146:149], v[122:125], v[162:165], v[146:149]
	v_mfma_f32_16x16x32_bf16 v[138:141], v[142:145], v[162:165], v[138:141]
	v_mfma_f32_16x16x32_bf16 v[102:105], v[122:125], v[170:173], v[102:105]
	v_mfma_f32_16x16x32_bf16 v[98:101], v[142:145], v[170:173], v[98:101]
	v_mfma_f32_16x16x32_bf16 v[86:89], v[122:125], v[178:181], v[86:89]
	v_mfma_f32_16x16x32_bf16 v[82:85], v[142:145], v[178:181], v[82:85]
	v_mfma_f32_16x16x32_bf16 v[70:73], v[122:125], v[186:189], v[70:73]
	v_mfma_f32_16x16x32_bf16 v[66:69], v[142:145], v[186:189], v[66:69]
	v_mfma_f32_16x16x32_bf16 v[146:149], v[126:129], v[166:169], v[146:149]
	v_mfma_f32_16x16x32_bf16 v[138:141], v[150:153], v[166:169], v[138:141]
	v_mfma_f32_16x16x32_bf16 v[102:105], v[126:129], v[174:177], v[102:105]
	v_mfma_f32_16x16x32_bf16 v[98:101], v[150:153], v[174:177], v[98:101]
	v_mfma_f32_16x16x32_bf16 v[86:89], v[126:129], v[182:185], v[86:89]
	v_mfma_f32_16x16x32_bf16 v[82:85], v[150:153], v[182:185], v[82:85]
	v_mfma_f32_16x16x32_bf16 v[70:73], v[126:129], v[190:193], v[70:73]
	v_mfma_f32_16x16x32_bf16 v[66:69], v[150:153], v[190:193], v[66:69]
	s_barrier
	s_add_i32 s85, s85, s34
	v_lshl_add_u64 v[194:195], s[30:31], 0, v[214:215]
	s_mov_b32 m0, s85
	ds_read_b128 v[162:165], v230 offset:16384
	ds_read_b128 v[166:169], v230 offset:17408
	ds_read_b128 v[170:173], v230 offset:18432
	ds_read_b128 v[174:177], v230 offset:19456
	ds_read_b128 v[178:181], v230 offset:20480
	ds_read_b128 v[182:185], v230 offset:21504
	ds_read_b128 v[186:189], v230 offset:22528
	ds_read_b128 v[190:193], v230 offset:23552
	global_load_lds_dwordx4 v[194:195], off
	s_add_i32 m0, s85, 0x2000
	s_add_u32 s94, s30, 0x20000
	v_lshl_add_u64 v[196:197], s[30:31], 0, v[210:211]
	s_addc_u32 s95, s31, 0
	s_add_i32 s85, s89, s34
	global_load_lds_dwordx4 v[196:197], off
	v_lshl_add_u64 v[198:199], s[94:95], 0, v[214:215]
	s_mov_b32 m0, s85
	v_lshl_add_u64 v[200:201], s[40:41], 0, v[212:213]
	global_load_lds_dwordx4 v[198:199], off
	v_lshl_add_u64 v[198:199], s[94:95], 0, v[210:211]
	s_add_i32 m0, s85, 0x2000
	s_nop 0
	global_load_lds_dwordx4 v[198:199], off
	v_lshl_add_u64 v[198:199], s[40:41], 0, v[216:217]
	s_mov_b32 m0, s35
	s_nop 0
	global_load_lds_dwordx4 v[198:199], off
	s_mov_b32 m0, s36
	s_nop 0
	global_load_lds_dwordx4 v[200:201], off
	s_waitcnt vmcnt(8)
	s_waitcnt lgkmcnt(0)
	s_barrier
; #define PG8_STAGE(bufoff, gbase, voff) do { _Pragma("unroll") for (int _i = 0; _i < 2; ++_i) \
;         __builtin_amdgcn_global_load_lds((const unsigned*)((const char*)(gbase) + (voff)[_i]), (PG8_LAS unsigned*)(lds + (bufoff) + ldsw + _i * 8192), 16, 0, 0); } while (0)
; #define PG8_LDA(dst, b, h) do { _Pragma("unroll") for (int m = 0; m < 4; ++m) _Pragma("unroll") for (int k = 0; k < 2; ++k) dst[m][k] = *(const PG8_LAS bf16x8*)(lds + PG8_SA(b, h) + aoff + m * 2048 + k * 1024); } while (0)
; #define PG8_LDB(dst, b, h) do { _Pragma("unroll") for (int n = 0; n < 2; ++n) _Pragma("unroll") for (int k = 0; k < 2; ++k) dst[n][k] = *(const PG8_LAS bf16x8*)(lds + PG8_SB(b, h) + boff + n * 2048 + k * 1024); } while (0)
; #define PG8_MMA(ai, bj, At, Bt) do { __builtin_amdgcn_s_setprio(1); _Pragma("unroll") for (int m = 0; m < 4; ++m) _Pragma("unroll") for (int n = 0; n < 2; ++n) _Pragma("unroll") for (int k = 0; k < 2; ++k) \
;         acc[ai][bj][m][n] = __builtin_amdgcn_mfma_f32_16x16x32_bf16(Bt[n][k], At[m][k], acc[ai][bj][m][n], 0, 0, 0); __builtin_amdgcn_s_setprio(0); } while (0)
; #define PG8_WAIT_V(n) asm volatile("s_waitcnt vmcnt(" #n ")" ::: "memory")
; #define PG8_WAIT_L(n) asm volatile("s_waitcnt lgkmcnt(" #n ")" ::: "memory")
; #define PG8_BAR __builtin_amdgcn_s_barrier()
; #define PG8_SCHED __builtin_amdgcn_sched_barrier(0)
; template <class Epi, class Sched, bool ALIGN_EPI = false, bool SP2 = false>
; __device__ __forceinline__ void gemm_phase(PG8_LAS unsigned char* lds, const Gemm g, const Sched& S, const Epi& E, int wave_s) {
;     ...
;             PG8_LDA(At, 0, 1); PG8_STAGE(PG8_SB(0, 0), b2, voffB); PG8_STAGE(PG8_SB(0, 1), b2 + hstepB, voffB); PG8_STAGE(PG8_SA(0, 0), a2, voffA);
;             PG8_WAIT_V(8); PG8_WAIT_L(0); PG8_BAR; PG8_MMA(1, 0, At, B0); PG8_MMA(1, 1, At, B1); PG8_BAR; PG8_SCHED;
;             PG8_LDB(B0, 1, 0); PG8_LDB(B1, 1, 1); PG8_SCHED; PG8_LDA(At, 1, 0); PG8_STAGE(PG8_SA(0, 1), a2 + hstepA, voffA);
;             PG8_WAIT_V(8); PG8_WAIT_L(0); PG8_BAR; PG8_MMA(0, 0, At, B0); PG8_MMA(0, 1, At, B1); PG8_BAR; PG8_SCHED;
	s_waitcnt lgkmcnt(0)
	v_mfma_f32_16x16x32_bf16 v[62:65], v[106:109], v[162:165], v[62:65]
	v_mfma_f32_16x16x32_bf16 v[58:61], v[114:117], v[162:165], v[58:61]
	v_mfma_f32_16x16x32_bf16 v[46:49], v[106:109], v[170:173], v[46:49]
	v_mfma_f32_16x16x32_bf16 v[42:45], v[114:117], v[170:173], v[42:45]
	v_mfma_f32_16x16x32_bf16 v[30:33], v[106:109], v[178:181], v[30:33]
	v_mfma_f32_16x16x32_bf16 v[26:29], v[114:117], v[178:181], v[26:29]
	v_mfma_f32_16x16x32_bf16 v[14:17], v[106:109], v[186:189], v[14:17]
	v_mfma_f32_16x16x32_bf16 v[10:13], v[114:117], v[186:189], v[10:13]
	v_mfma_f32_16x16x32_bf16 v[62:65], v[110:113], v[166:169], v[62:65]
	v_mfma_f32_16x16x32_bf16 v[58:61], v[118:121], v[166:169], v[58:61]
	v_mfma_f32_16x16x32_bf16 v[46:49], v[110:113], v[174:177], v[46:49]
	v_mfma_f32_16x16x32_bf16 v[42:45], v[118:121], v[174:177], v[42:45]
	v_mfma_f32_16x16x32_bf16 v[30:33], v[110:113], v[182:185], v[30:33]
	v_mfma_f32_16x16x32_bf16 v[26:29], v[118:121], v[182:185], v[26:29]
	v_mfma_f32_16x16x32_bf16 v[14:17], v[110:113], v[190:193], v[14:17]
	v_mfma_f32_16x16x32_bf16 v[10:13], v[118:121], v[190:193], v[10:13]
	v_mfma_f32_16x16x32_bf16 v[54:57], v[122:125], v[162:165], v[54:57]
	v_mfma_f32_16x16x32_bf16 v[50:53], v[142:145], v[162:165], v[50:53]
	v_mfma_f32_16x16x32_bf16 v[38:41], v[122:125], v[170:173], v[38:41]
	v_mfma_f32_16x16x32_bf16 v[34:37], v[142:145], v[170:173], v[34:37]
	v_mfma_f32_16x16x32_bf16 v[22:25], v[122:125], v[178:181], v[22:25]
	v_mfma_f32_16x16x32_bf16 v[18:21], v[142:145], v[178:181], v[18:21]
	v_mfma_f32_16x16x32_bf16 v[6:9], v[122:125], v[186:189], v[6:9]
	v_mfma_f32_16x16x32_bf16 v[2:5], v[142:145], v[186:189], v[2:5]
	v_mfma_f32_16x16x32_bf16 v[54:57], v[126:129], v[166:169], v[54:57]
	v_mfma_f32_16x16x32_bf16 v[50:53], v[150:153], v[166:169], v[50:53]
	v_mfma_f32_16x16x32_bf16 v[38:41], v[126:129], v[174:177], v[38:41]
	v_mfma_f32_16x16x32_bf16 v[34:37], v[150:153], v[174:177], v[34:37]
	v_mfma_f32_16x16x32_bf16 v[22:25], v[126:129], v[182:185], v[22:25]
	v_mfma_f32_16x16x32_bf16 v[18:21], v[150:153], v[182:185], v[18:21]
	v_mfma_f32_16x16x32_bf16 v[6:9], v[126:129], v[190:193], v[6:9]
	v_mfma_f32_16x16x32_bf16 v[2:5], v[150:153], v[190:193], v[2:5]
	s_barrier
	s_add_i32 s85, 0, 0x18000
	s_add_i32 s89, 0, 0x1c000
	v_add_u32_e32 v118, s85, v229
	v_add_u32_e32 v150, s89, v229
	ds_read_b128 v[106:109], v118
	ds_read_b128 v[110:113], v118 offset:1024
	ds_read_b128 v[114:117], v118 offset:2048
	ds_read_b128 v[118:121], v118 offset:3072
	ds_read_b128 v[122:125], v150
	ds_read_b128 v[126:129], v150 offset:1024
	ds_read_b128 v[142:145], v150 offset:2048
	ds_read_b128 v[150:153], v150 offset:3072
	s_add_u32 s40, s40, 0x80000
	s_addc_u32 s41, s41, 0
	s_mov_b32 m0, s37
	v_lshl_add_u64 v[202:203], s[40:41], 0, v[216:217]
	ds_read_b128 v[162:165], v230 offset:32768
	ds_read_b128 v[166:169], v230 offset:33792
	ds_read_b128 v[170:173], v230 offset:34816
	ds_read_b128 v[174:177], v230 offset:35840
	ds_read_b128 v[178:181], v230 offset:36864
	ds_read_b128 v[182:185], v230 offset:37888
	ds_read_b128 v[186:189], v230 offset:38912
	ds_read_b128 v[190:193], v230 offset:39936
	global_load_lds_dwordx4 v[202:203], off
	v_lshl_add_u64 v[202:203], s[40:41], 0, v[212:213]
	s_mov_b32 m0, s42
	s_nop 0
	global_load_lds_dwordx4 v[202:203], off
	s_waitcnt vmcnt(8)
	s_waitcnt lgkmcnt(0)
	s_barrier
	s_waitcnt lgkmcnt(0)
	v_mfma_f32_16x16x32_bf16 v[158:161], v[106:109], v[162:165], v[158:161]
	v_mfma_f32_16x16x32_bf16 v[154:157], v[114:117], v[162:165], v[154:157]
	v_mfma_f32_16x16x32_bf16 v[134:137], v[106:109], v[170:173], v[134:137]
	v_mfma_f32_16x16x32_bf16 v[130:133], v[114:117], v[170:173], v[130:133]
	v_mfma_f32_16x16x32_bf16 v[94:97], v[106:109], v[178:181], v[94:97]
	v_mfma_f32_16x16x32_bf16 v[90:93], v[114:117], v[178:181], v[90:93]
	v_mfma_f32_16x16x32_bf16 v[78:81], v[106:109], v[186:189], v[78:81]
	v_mfma_f32_16x16x32_bf16 v[74:77], v[114:117], v[186:189], v[74:77]
	v_mfma_f32_16x16x32_bf16 v[158:161], v[110:113], v[166:169], v[158:161]
	v_mfma_f32_16x16x32_bf16 v[154:157], v[118:121], v[166:169], v[154:157]
	v_mfma_f32_16x16x32_bf16 v[134:137], v[110:113], v[174:177], v[134:137]
	v_mfma_f32_16x16x32_bf16 v[130:133], v[118:121], v[174:177], v[130:133]
	v_mfma_f32_16x16x32_bf16 v[94:97], v[110:113], v[182:185], v[94:97]
	v_mfma_f32_16x16x32_bf16 v[90:93], v[118:121], v[182:185], v[90:93]
	v_mfma_f32_16x16x32_bf16 v[78:81], v[110:113], v[190:193], v[78:81]
	v_mfma_f32_16x16x32_bf16 v[74:77], v[118:121], v[190:193], v[74:77]
	v_mfma_f32_16x16x32_bf16 v[146:149], v[122:125], v[162:165], v[146:149]
	v_mfma_f32_16x16x32_bf16 v[138:141], v[142:145], v[162:165], v[138:141]
	v_mfma_f32_16x16x32_bf16 v[102:105], v[122:125], v[170:173], v[102:105]
	v_mfma_f32_16x16x32_bf16 v[98:101], v[142:145], v[170:173], v[98:101]
	v_mfma_f32_16x16x32_bf16 v[86:89], v[122:125], v[178:181], v[86:89]
	v_mfma_f32_16x16x32_bf16 v[82:85], v[142:145], v[178:181], v[82:85]
	v_mfma_f32_16x16x32_bf16 v[70:73], v[122:125], v[186:189], v[70:73]
	v_mfma_f32_16x16x32_bf16 v[66:69], v[142:145], v[186:189], v[66:69]
	v_mfma_f32_16x16x32_bf16 v[146:149], v[126:129], v[166:169], v[146:149]
	v_mfma_f32_16x16x32_bf16 v[138:141], v[150:153], v[166:169], v[138:141]
	v_mfma_f32_16x16x32_bf16 v[102:105], v[126:129], v[174:177], v[102:105]
	v_mfma_f32_16x16x32_bf16 v[98:101], v[150:153], v[174:177], v[98:101]
	v_mfma_f32_16x16x32_bf16 v[86:89], v[126:129], v[182:185], v[86:89]
	v_mfma_f32_16x16x32_bf16 v[82:85], v[150:153], v[182:185], v[82:85]
	v_mfma_f32_16x16x32_bf16 v[70:73], v[126:129], v[190:193], v[70:73]
	v_mfma_f32_16x16x32_bf16 v[66:69], v[150:153], v[190:193], v[66:69]
	s_barrier
; #define PG8_STAGE(bufoff, gbase, voff) do { _Pragma("unroll") for (int _i = 0; _i < 2; ++_i) \
;         __builtin_amdgcn_global_load_lds((const unsigned*)((const char*)(gbase) + (voff)[_i]), (PG8_LAS unsigned*)(lds + (bufoff) + ldsw + _i * 8192), 16, 0, 0); } while (0)
; #define PG8_LDA(dst, b, h) do { _Pragma("unroll") for (int m = 0; m < 4; ++m) _Pragma("unroll") for (int k = 0; k < 2; ++k) dst[m][k] = *(const PG8_LAS bf16x8*)(lds + PG8_SA(b, h) + aoff + m * 2048 + k * 1024); } while (0)
; #define PG8_MMA(ai, bj, At, Bt) do { __builtin_amdgcn_s_setprio(1); _Pragma("unroll") for (int m = 0; m < 4; ++m) _Pragma("unroll") for (int n = 0; n < 2; ++n) _Pragma("unroll") for (int k = 0; k < 2; ++k) \
;         acc[ai][bj][m][n] = __builtin_amdgcn_mfma_f32_16x16x32_bf16(Bt[n][k], At[m][k], acc[ai][bj][m][n], 0, 0, 0); __builtin_amdgcn_s_setprio(0); } while (0)
; #define PG8_WAIT_V(n) asm volatile("s_waitcnt vmcnt(" #n ")" ::: "memory")
; #define PG8_WAIT_L(n) asm volatile("s_waitcnt lgkmcnt(" #n ")" ::: "memory")
; #define PG8_BAR __builtin_amdgcn_s_barrier()
; #define PG8_SCHED __builtin_amdgcn_sched_barrier(0)
; template <class Epi, class Sched, bool ALIGN_EPI = false, bool SP2 = false>
; __device__ __forceinline__ void gemm_phase(PG8_LAS unsigned char* lds, const Gemm g, const Sched& S, const Epi& E, int wave_s) {
;     ...
;         for (int t = 0; t < nt; t += 2) {
;             const bool last = (t == nt - 2);
;             const char* a1 = cA + (size_t)(t + 1) * kstep;
;             const char* a2 = last ? nA : cA + (size_t)(t + 2) * kstep; const char* b2 = last ? nB : cB + (size_t)(t + 2) * kstep;
;     ...
;             PG8_LDA(At, 1, 1); PG8_STAGE(PG8_SB(1, 0), b3, voffB); PG8_STAGE(PG8_SB(1, 1), b3 + hstepB, voffB); PG8_STAGE(PG8_SA(1, 0), a3, voffA);
;             PG8_WAIT_V(8); PG8_WAIT_L(0); PG8_BAR; PG8_MMA(1, 0, At, B0); PG8_MMA(1, 1, At, B1); PG8_BAR; PG8_SCHED;
	s_add_i32 s40, s85, s34
	v_lshl_add_u64 v[194:195], v[194:195], 0, s[60:61]
	s_mov_b32 m0, s40
	ds_read_b128 v[162:165], v230 offset:49152
	ds_read_b128 v[166:169], v230 offset:50176
	ds_read_b128 v[170:173], v230 offset:51200
	ds_read_b128 v[174:177], v230 offset:52224
	ds_read_b128 v[178:181], v230 offset:53248
	ds_read_b128 v[182:185], v230 offset:54272
	ds_read_b128 v[186:189], v230 offset:55296
	ds_read_b128 v[190:193], v230 offset:56320
	global_load_lds_dwordx4 v[194:195], off
	s_add_i32 m0, s40, 0x2000
	s_add_u32 s30, s30, 0x20080
	v_lshl_add_u64 v[194:195], v[196:197], 0, s[60:61]
	s_addc_u32 s31, s31, 0
	s_add_i32 s40, s89, s34
	global_load_lds_dwordx4 v[194:195], off
	v_lshl_add_u64 v[194:195], s[30:31], 0, v[214:215]
	s_mov_b32 m0, s40
	s_nop 0
	global_load_lds_dwordx4 v[194:195], off
	v_lshl_add_u64 v[194:195], s[30:31], 0, v[210:211]
	s_add_i32 m0, s40, 0x2000
	s_nop 0
	global_load_lds_dwordx4 v[194:195], off
	v_lshl_add_u64 v[194:195], v[198:199], 0, s[60:61]
	s_mov_b32 m0, s46
	s_nop 0
	global_load_lds_dwordx4 v[194:195], off
	v_lshl_add_u64 v[194:195], v[200:201], 0, s[60:61]
	s_mov_b32 m0, s47
	s_nop 0
	global_load_lds_dwordx4 v[194:195], off
	s_waitcnt vmcnt(8)
	s_waitcnt lgkmcnt(0)
	s_barrier
	s_waitcnt lgkmcnt(0)
	v_mfma_f32_16x16x32_bf16 v[62:65], v[106:109], v[162:165], v[62:65]
	v_mfma_f32_16x16x32_bf16 v[58:61], v[114:117], v[162:165], v[58:61]
	v_mfma_f32_16x16x32_bf16 v[46:49], v[106:109], v[170:173], v[46:49]
	v_mfma_f32_16x16x32_bf16 v[42:45], v[114:117], v[170:173], v[42:45]
	v_mfma_f32_16x16x32_bf16 v[30:33], v[106:109], v[178:181], v[30:33]
	v_mfma_f32_16x16x32_bf16 v[26:29], v[114:117], v[178:181], v[26:29]
	v_mfma_f32_16x16x32_bf16 v[14:17], v[106:109], v[186:189], v[14:17]
	v_mfma_f32_16x16x32_bf16 v[10:13], v[114:117], v[186:189], v[10:13]
	v_mfma_f32_16x16x32_bf16 v[62:65], v[110:113], v[166:169], v[62:65]
	v_mfma_f32_16x16x32_bf16 v[58:61], v[118:121], v[166:169], v[58:61]
	v_mfma_f32_16x16x32_bf16 v[46:49], v[110:113], v[174:177], v[46:49]
	v_mfma_f32_16x16x32_bf16 v[42:45], v[118:121], v[174:177], v[42:45]
	v_mfma_f32_16x16x32_bf16 v[30:33], v[110:113], v[182:185], v[30:33]
	v_mfma_f32_16x16x32_bf16 v[26:29], v[118:121], v[182:185], v[26:29]
	v_mfma_f32_16x16x32_bf16 v[14:17], v[110:113], v[190:193], v[14:17]
	v_mfma_f32_16x16x32_bf16 v[10:13], v[118:121], v[190:193], v[10:13]
	v_mfma_f32_16x16x32_bf16 v[54:57], v[122:125], v[162:165], v[54:57]
	v_mfma_f32_16x16x32_bf16 v[50:53], v[142:145], v[162:165], v[50:53]
	v_mfma_f32_16x16x32_bf16 v[38:41], v[122:125], v[170:173], v[38:41]
	v_mfma_f32_16x16x32_bf16 v[34:37], v[142:145], v[170:173], v[34:37]
	v_mfma_f32_16x16x32_bf16 v[22:25], v[122:125], v[178:181], v[22:25]
	v_mfma_f32_16x16x32_bf16 v[18:21], v[142:145], v[178:181], v[18:21]
	v_mfma_f32_16x16x32_bf16 v[6:9], v[122:125], v[186:189], v[6:9]
	v_mfma_f32_16x16x32_bf16 v[2:5], v[142:145], v[186:189], v[2:5]
	v_mfma_f32_16x16x32_bf16 v[54:57], v[126:129], v[166:169], v[54:57]
	v_mfma_f32_16x16x32_bf16 v[50:53], v[150:153], v[166:169], v[50:53]
	v_mfma_f32_16x16x32_bf16 v[38:41], v[126:129], v[174:177], v[38:41]
	v_mfma_f32_16x16x32_bf16 v[34:37], v[150:153], v[174:177], v[34:37]
	v_mfma_f32_16x16x32_bf16 v[22:25], v[126:129], v[182:185], v[22:25]
	v_mfma_f32_16x16x32_bf16 v[18:21], v[150:153], v[182:185], v[18:21]
	v_mfma_f32_16x16x32_bf16 v[6:9], v[126:129], v[190:193], v[6:9]
	v_mfma_f32_16x16x32_bf16 v[2:5], v[150:153], v[190:193], v[2:5]
	s_barrier
	s_add_i32 s84, s84, 2
	s_add_u32 s4, s4, 0x100
	s_addc_u32 s5, s5, 0
	s_add_u32 s29, s29, 0x100
	s_addc_u32 s81, s81, 0
	s_cmp_gt_u32 s84, 5
	s_cbranch_scc0 .LBB0_314
	s_and_b64 vcc, exec, s[20:21]
	s_cbranch_vccz .LBB0_317
	s_barrier

; #define PG8_STAGE(bufoff, gbase, voff) do { _Pragma("unroll") for (int _i = 0; _i < 2; ++_i) \
;         __builtin_amdgcn_global_load_lds((const unsigned*)((const char*)(gbase) + (voff)[_i]), (PG8_LAS unsigned*)(lds + (bufoff) + ldsw + _i * 8192), 16, 0, 0); } while (0)
; #define PG8_LDA(dst, b, h) do { _Pragma("unroll") for (int m = 0; m < 4; ++m) _Pragma("unroll") for (int k = 0; k < 2; ++k) dst[m][k] = *(const PG8_LAS bf16x8*)(lds + PG8_SA(b, h) + aoff + m * 2048 + k * 1024); } while (0)
; #define PG8_LDB(dst, b, h) do { _Pragma("unroll") for (int n = 0; n < 2; ++n) _Pragma("unroll") for (int k = 0; k < 2; ++k) dst[n][k] = *(const PG8_LAS bf16x8*)(lds + PG8_SB(b, h) + boff + n * 2048 + k * 1024); } while (0)
; #define PG8_MMA(ai, bj, At, Bt) do { __builtin_amdgcn_s_setprio(1); _Pragma("unroll") for (int m = 0; m < 4; ++m) _Pragma("unroll") for (int n = 0; n < 2; ++n) _Pragma("unroll") for (int k = 0; k < 2; ++k) \
;         acc[ai][bj][m][n] = __builtin_amdgcn_mfma_f32_16x16x32_bf16(Bt[n][k], At[m][k], acc[ai][bj][m][n], 0, 0, 0); __builtin_amdgcn_s_setprio(0); } while (0)
; #define PG8_WAIT_V(n) asm volatile("s_waitcnt vmcnt(" #n ")" ::: "memory")
; #define PG8_WAIT_L(n) asm volatile("s_waitcnt lgkmcnt(" #n ")" ::: "memory")
; #define PG8_BAR __builtin_amdgcn_s_barrier()
; #define PG8_SCHED __builtin_amdgcn_sched_barrier(0)
; template <class Epi, class Sched, bool ALIGN_EPI = false, bool SP2 = false>
; __device__ __forceinline__ void gemm_phase(PG8_LAS unsigned char* lds, const Gemm g, const Sched& S, const Epi& E, int wave_s) {
;     ...
;             PG8_LDB(B0, 0, 0); PG8_LDB(B1, 0, 1); PG8_SCHED; PG8_LDA(At, 0, 0); PG8_STAGE(PG8_SA(1, 1), a1 + hstepA, voffA);
;             PG8_WAIT_V(8); PG8_WAIT_L(0); PG8_BAR; PG8_MMA(0, 0, At, B0); PG8_MMA(0, 1, At, B1); PG8_BAR; PG8_SCHED;
;             PG8_LDA(At, 0, 1); PG8_STAGE(PG8_SB(0, 0), b2, voffB); PG8_STAGE(PG8_SB(0, 1), b2 + hstepB, voffB); PG8_STAGE(PG8_SA(0, 0), a2, voffA);
;             PG8_WAIT_V(8); PG8_WAIT_L(0); PG8_BAR; PG8_MMA(1, 0, At, B0); PG8_MMA(1, 1, At, B1); PG8_BAR; PG8_SCHED;
.LBB0_412:
	s_add_i32 s95, 0, 0x10000
	v_add_u32_e32 v149, s95, v147
	s_add_i32 vcc_lo, 0, 0x14000
	ds_read_b128 v[142:145], v149
	ds_read_b128 v[150:153], v149 offset:1024
	ds_read_b128 v[154:157], v149 offset:2048
	ds_read_b128 v[158:161], v149 offset:3072
	v_add_u32_e32 v149, vcc_lo, v147
	ds_read_b128 v[162:165], v149
	ds_read_b128 v[166:169], v149 offset:1024
	ds_read_b128 v[170:173], v149 offset:2048
	ds_read_b128 v[174:177], v149 offset:3072
	s_add_u32 s30, s4, 0xfff80080
	s_addc_u32 s31, s5, -1
	s_cmp_eq_u32 s94, 28
	s_cselect_b32 s41, s27, s31
	s_cselect_b32 s40, s26, s30
	s_cselect_b32 s31, s2, s21
	s_cselect_b32 s30, s3, s15
	v_lshl_add_u64 v[210:211], s[4:5], 0, v[138:139]
	s_add_i32 m0, s35, 0xc000
	ds_read_b128 v[178:181], v148
	ds_read_b128 v[182:185], v148 offset:1024
	ds_read_b128 v[186:189], v148 offset:2048
	ds_read_b128 v[190:193], v148 offset:3072
	ds_read_b128 v[194:197], v148 offset:4096
	ds_read_b128 v[198:201], v148 offset:5120
	ds_read_b128 v[202:205], v148 offset:6144
	ds_read_b128 v[206:209], v148 offset:7168
	global_load_lds_dwordx4 v[210:211], off
	v_lshl_add_u64 v[210:211], s[4:5], 0, v[140:141]
	s_add_i32 m0, s35, 0xe000
	s_nop 0
	global_load_lds_dwordx4 v[210:211], off
	s_waitcnt vmcnt(8)
	s_waitcnt lgkmcnt(0)
	s_barrier
	s_waitcnt lgkmcnt(0)
	v_mfma_f32_16x16x32_bf16 v[126:129], v[142:145], v[178:181], v[126:129]
	v_mfma_f32_16x16x32_bf16 v[122:125], v[154:157], v[178:181], v[122:125]
	v_mfma_f32_16x16x32_bf16 v[110:113], v[142:145], v[186:189], v[110:113]
	v_mfma_f32_16x16x32_bf16 v[106:109], v[154:157], v[186:189], v[106:109]
	v_mfma_f32_16x16x32_bf16 v[94:97], v[142:145], v[194:197], v[94:97]
	v_mfma_f32_16x16x32_bf16 v[90:93], v[154:157], v[194:197], v[90:93]
	v_mfma_f32_16x16x32_bf16 v[78:81], v[142:145], v[202:205], v[78:81]
	v_mfma_f32_16x16x32_bf16 v[74:77], v[154:157], v[202:205], v[74:77]
	v_mfma_f32_16x16x32_bf16 v[126:129], v[150:153], v[182:185], v[126:129]
	v_mfma_f32_16x16x32_bf16 v[122:125], v[158:161], v[182:185], v[122:125]
	v_mfma_f32_16x16x32_bf16 v[110:113], v[150:153], v[190:193], v[110:113]
	v_mfma_f32_16x16x32_bf16 v[106:109], v[158:161], v[190:193], v[106:109]
	v_mfma_f32_16x16x32_bf16 v[94:97], v[150:153], v[198:201], v[94:97]
	v_mfma_f32_16x16x32_bf16 v[90:93], v[158:161], v[198:201], v[90:93]
	v_mfma_f32_16x16x32_bf16 v[78:81], v[150:153], v[206:209], v[78:81]
	v_mfma_f32_16x16x32_bf16 v[74:77], v[158:161], v[206:209], v[74:77]
	v_mfma_f32_16x16x32_bf16 v[118:121], v[162:165], v[178:181], v[118:121]
	v_mfma_f32_16x16x32_bf16 v[114:117], v[170:173], v[178:181], v[114:117]
	v_mfma_f32_16x16x32_bf16 v[102:105], v[162:165], v[186:189], v[102:105]
	v_mfma_f32_16x16x32_bf16 v[98:101], v[170:173], v[186:189], v[98:101]
	v_mfma_f32_16x16x32_bf16 v[86:89], v[162:165], v[194:197], v[86:89]
	v_mfma_f32_16x16x32_bf16 v[82:85], v[170:173], v[194:197], v[82:85]
	v_mfma_f32_16x16x32_bf16 v[70:73], v[162:165], v[202:205], v[70:73]
	v_mfma_f32_16x16x32_bf16 v[66:69], v[170:173], v[202:205], v[66:69]
	v_mfma_f32_16x16x32_bf16 v[118:121], v[166:169], v[182:185], v[118:121]
	v_mfma_f32_16x16x32_bf16 v[114:117], v[174:177], v[182:185], v[114:117]
	v_mfma_f32_16x16x32_bf16 v[102:105], v[166:169], v[190:193], v[102:105]
	v_mfma_f32_16x16x32_bf16 v[98:101], v[174:177], v[190:193], v[98:101]
	v_mfma_f32_16x16x32_bf16 v[86:89], v[166:169], v[198:201], v[86:89]
	v_mfma_f32_16x16x32_bf16 v[82:85], v[174:177], v[198:201], v[82:85]
	v_mfma_f32_16x16x32_bf16 v[70:73], v[166:169], v[206:209], v[70:73]
	v_mfma_f32_16x16x32_bf16 v[66:69], v[174:177], v[206:209], v[66:69]
	s_barrier
	s_add_i32 s95, s95, s34
	v_lshl_add_u64 v[210:211], s[30:31], 0, v[132:133]
	s_mov_b32 m0, s95
	ds_read_b128 v[178:181], v148 offset:16384
	ds_read_b128 v[182:185], v148 offset:17408
	ds_read_b128 v[186:189], v148 offset:18432
	ds_read_b128 v[190:193], v148 offset:19456
	ds_read_b128 v[194:197], v148 offset:20480
	ds_read_b128 v[198:201], v148 offset:21504
	ds_read_b128 v[202:205], v148 offset:22528
	ds_read_b128 v[206:209], v148 offset:23552
	global_load_lds_dwordx4 v[210:211], off
	s_add_i32 m0, s95, 0x2000
	s_add_u32 s96, s30, 0x80000
	v_lshl_add_u64 v[212:213], s[30:31], 0, v[136:137]
	s_addc_u32 s97, s31, 0
	s_add_i32 s95, vcc_lo, s34
	global_load_lds_dwordx4 v[212:213], off
	v_lshl_add_u64 v[214:215], s[96:97], 0, v[132:133]
	s_mov_b32 m0, s95
	v_lshl_add_u64 v[216:217], s[40:41], 0, v[134:135]
	global_load_lds_dwordx4 v[214:215], off
	v_lshl_add_u64 v[214:215], s[96:97], 0, v[136:137]
	s_add_i32 m0, s95, 0x2000
	s_nop 0
	global_load_lds_dwordx4 v[214:215], off
	v_lshl_add_u64 v[214:215], s[40:41], 0, v[130:131]
	s_mov_b32 m0, s35
	s_nop 0
	global_load_lds_dwordx4 v[214:215], off
	s_mov_b32 m0, s36
	s_nop 0
	global_load_lds_dwordx4 v[216:217], off
	s_waitcnt vmcnt(8)
	s_waitcnt lgkmcnt(0)
	s_barrier
; #define PG8_STAGE(bufoff, gbase, voff) do { _Pragma("unroll") for (int _i = 0; _i < 2; ++_i) \
;         __builtin_amdgcn_global_load_lds((const unsigned*)((const char*)(gbase) + (voff)[_i]), (PG8_LAS unsigned*)(lds + (bufoff) + ldsw + _i * 8192), 16, 0, 0); } while (0)
; #define PG8_LDA(dst, b, h) do { _Pragma("unroll") for (int m = 0; m < 4; ++m) _Pragma("unroll") for (int k = 0; k < 2; ++k) dst[m][k] = *(const PG8_LAS bf16x8*)(lds + PG8_SA(b, h) + aoff + m * 2048 + k * 1024); } while (0)
; #define PG8_LDB(dst, b, h) do { _Pragma("unroll") for (int n = 0; n < 2; ++n) _Pragma("unroll") for (int k = 0; k < 2; ++k) dst[n][k] = *(const PG8_LAS bf16x8*)(lds + PG8_SB(b, h) + boff + n * 2048 + k * 1024); } while (0)
; #define PG8_MMA(ai, bj, At, Bt) do { __builtin_amdgcn_s_setprio(1); _Pragma("unroll") for (int m = 0; m < 4; ++m) _Pragma("unroll") for (int n = 0; n < 2; ++n) _Pragma("unroll") for (int k = 0; k < 2; ++k) \
;         acc[ai][bj][m][n] = __builtin_amdgcn_mfma_f32_16x16x32_bf16(Bt[n][k], At[m][k], acc[ai][bj][m][n], 0, 0, 0); __builtin_amdgcn_s_setprio(0); } while (0)
; #define PG8_WAIT_V(n) asm volatile("s_waitcnt vmcnt(" #n ")" ::: "memory")
; #define PG8_WAIT_L(n) asm volatile("s_waitcnt lgkmcnt(" #n ")" ::: "memory")
; #define PG8_BAR __builtin_amdgcn_s_barrier()
; #define PG8_SCHED __builtin_amdgcn_sched_barrier(0)
; template <class Epi, class Sched, bool ALIGN_EPI = false, bool SP2 = false>
; __device__ __forceinline__ void gemm_phase(PG8_LAS unsigned char* lds, const Gemm g, const Sched& S, const Epi& E, int wave_s) {
;     ...
;             PG8_LDA(At, 0, 1); PG8_STAGE(PG8_SB(0, 0), b2, voffB); PG8_STAGE(PG8_SB(0, 1), b2 + hstepB, voffB); PG8_STAGE(PG8_SA(0, 0), a2, voffA);
;             PG8_WAIT_V(8); PG8_WAIT_L(0); PG8_BAR; PG8_MMA(1, 0, At, B0); PG8_MMA(1, 1, At, B1); PG8_BAR; PG8_SCHED;
;             PG8_LDB(B0, 1, 0); PG8_LDB(B1, 1, 1); PG8_SCHED; PG8_LDA(At, 1, 0); PG8_STAGE(PG8_SA(0, 1), a2 + hstepA, voffA);
;             PG8_WAIT_V(8); PG8_WAIT_L(0); PG8_BAR; PG8_MMA(0, 0, At, B0); PG8_MMA(0, 1, At, B1); PG8_BAR; PG8_SCHED;
	s_waitcnt lgkmcnt(0)
	v_mfma_f32_16x16x32_bf16 v[62:65], v[142:145], v[178:181], v[62:65]
	v_mfma_f32_16x16x32_bf16 v[58:61], v[154:157], v[178:181], v[58:61]
	v_mfma_f32_16x16x32_bf16 v[46:49], v[142:145], v[186:189], v[46:49]
	v_mfma_f32_16x16x32_bf16 v[42:45], v[154:157], v[186:189], v[42:45]
	v_mfma_f32_16x16x32_bf16 v[30:33], v[142:145], v[194:197], v[30:33]
	v_mfma_f32_16x16x32_bf16 v[26:29], v[154:157], v[194:197], v[26:29]
	v_mfma_f32_16x16x32_bf16 v[14:17], v[142:145], v[202:205], v[14:17]
	v_mfma_f32_16x16x32_bf16 v[10:13], v[154:157], v[202:205], v[10:13]
	v_mfma_f32_16x16x32_bf16 v[62:65], v[150:153], v[182:185], v[62:65]
	v_mfma_f32_16x16x32_bf16 v[58:61], v[158:161], v[182:185], v[58:61]
	v_mfma_f32_16x16x32_bf16 v[46:49], v[150:153], v[190:193], v[46:49]
	v_mfma_f32_16x16x32_bf16 v[42:45], v[158:161], v[190:193], v[42:45]
	v_mfma_f32_16x16x32_bf16 v[30:33], v[150:153], v[198:201], v[30:33]
	v_mfma_f32_16x16x32_bf16 v[26:29], v[158:161], v[198:201], v[26:29]
	v_mfma_f32_16x16x32_bf16 v[14:17], v[150:153], v[206:209], v[14:17]
	v_mfma_f32_16x16x32_bf16 v[10:13], v[158:161], v[206:209], v[10:13]
	v_mfma_f32_16x16x32_bf16 v[54:57], v[162:165], v[178:181], v[54:57]
	v_mfma_f32_16x16x32_bf16 v[50:53], v[170:173], v[178:181], v[50:53]
	v_mfma_f32_16x16x32_bf16 v[38:41], v[162:165], v[186:189], v[38:41]
	v_mfma_f32_16x16x32_bf16 v[34:37], v[170:173], v[186:189], v[34:37]
	v_mfma_f32_16x16x32_bf16 v[22:25], v[162:165], v[194:197], v[22:25]
	v_mfma_f32_16x16x32_bf16 v[18:21], v[170:173], v[194:197], v[18:21]
	v_mfma_f32_16x16x32_bf16 v[6:9], v[162:165], v[202:205], v[6:9]
	v_mfma_f32_16x16x32_bf16 v[2:5], v[170:173], v[202:205], v[2:5]
	v_mfma_f32_16x16x32_bf16 v[54:57], v[166:169], v[182:185], v[54:57]
	v_mfma_f32_16x16x32_bf16 v[50:53], v[174:177], v[182:185], v[50:53]
	v_mfma_f32_16x16x32_bf16 v[38:41], v[166:169], v[190:193], v[38:41]
	v_mfma_f32_16x16x32_bf16 v[34:37], v[174:177], v[190:193], v[34:37]
	v_mfma_f32_16x16x32_bf16 v[22:25], v[166:169], v[198:201], v[22:25]
	v_mfma_f32_16x16x32_bf16 v[18:21], v[174:177], v[198:201], v[18:21]
	v_mfma_f32_16x16x32_bf16 v[6:9], v[166:169], v[206:209], v[6:9]
	v_mfma_f32_16x16x32_bf16 v[2:5], v[174:177], v[206:209], v[2:5]
	s_barrier
	s_add_i32 s95, 0, 0x18000
	v_add_u32_e32 v149, s95, v147
	s_add_i32 s96, 0, 0x1c000
	ds_read_b128 v[142:145], v149
	ds_read_b128 v[150:153], v149 offset:1024
	ds_read_b128 v[154:157], v149 offset:2048
	ds_read_b128 v[158:161], v149 offset:3072
	v_add_u32_e32 v149, s96, v147
	ds_read_b128 v[162:165], v149
	ds_read_b128 v[166:169], v149 offset:1024
	ds_read_b128 v[170:173], v149 offset:2048
	ds_read_b128 v[174:177], v149 offset:3072
	s_add_u32 s40, s40, 0x80000
	s_addc_u32 s41, s41, 0
	s_mov_b32 m0, s37
	v_lshl_add_u64 v[218:219], s[40:41], 0, v[130:131]
	ds_read_b128 v[178:181], v148 offset:32768
	ds_read_b128 v[182:185], v148 offset:33792
	ds_read_b128 v[186:189], v148 offset:34816
	ds_read_b128 v[190:193], v148 offset:35840
	ds_read_b128 v[194:197], v148 offset:36864
	ds_read_b128 v[198:201], v148 offset:37888
	ds_read_b128 v[202:205], v148 offset:38912
	ds_read_b128 v[206:209], v148 offset:39936
	global_load_lds_dwordx4 v[218:219], off
	v_lshl_add_u64 v[218:219], s[40:41], 0, v[134:135]
	s_mov_b32 m0, s42
	s_nop 0
	global_load_lds_dwordx4 v[218:219], off
	s_waitcnt vmcnt(8)
	s_waitcnt lgkmcnt(0)
	s_barrier
	s_waitcnt lgkmcnt(0)
	v_mfma_f32_16x16x32_bf16 v[126:129], v[142:145], v[178:181], v[126:129]
	v_mfma_f32_16x16x32_bf16 v[122:125], v[154:157], v[178:181], v[122:125]
	v_mfma_f32_16x16x32_bf16 v[110:113], v[142:145], v[186:189], v[110:113]
	v_mfma_f32_16x16x32_bf16 v[106:109], v[154:157], v[186:189], v[106:109]
	v_mfma_f32_16x16x32_bf16 v[94:97], v[142:145], v[194:197], v[94:97]
	v_mfma_f32_16x16x32_bf16 v[90:93], v[154:157], v[194:197], v[90:93]
	v_mfma_f32_16x16x32_bf16 v[78:81], v[142:145], v[202:205], v[78:81]
	v_mfma_f32_16x16x32_bf16 v[74:77], v[154:157], v[202:205], v[74:77]
	v_mfma_f32_16x16x32_bf16 v[126:129], v[150:153], v[182:185], v[126:129]
	v_mfma_f32_16x16x32_bf16 v[122:125], v[158:161], v[182:185], v[122:125]
	v_mfma_f32_16x16x32_bf16 v[110:113], v[150:153], v[190:193], v[110:113]
	v_mfma_f32_16x16x32_bf16 v[106:109], v[158:161], v[190:193], v[106:109]
	v_mfma_f32_16x16x32_bf16 v[94:97], v[150:153], v[198:201], v[94:97]
	v_mfma_f32_16x16x32_bf16 v[90:93], v[158:161], v[198:201], v[90:93]
	v_mfma_f32_16x16x32_bf16 v[78:81], v[150:153], v[206:209], v[78:81]
	v_mfma_f32_16x16x32_bf16 v[74:77], v[158:161], v[206:209], v[74:77]
	v_mfma_f32_16x16x32_bf16 v[118:121], v[162:165], v[178:181], v[118:121]
	v_mfma_f32_16x16x32_bf16 v[114:117], v[170:173], v[178:181], v[114:117]
	v_mfma_f32_16x16x32_bf16 v[102:105], v[162:165], v[186:189], v[102:105]
	v_mfma_f32_16x16x32_bf16 v[98:101], v[170:173], v[186:189], v[98:101]
	v_mfma_f32_16x16x32_bf16 v[86:89], v[162:165], v[194:197], v[86:89]
	v_mfma_f32_16x16x32_bf16 v[82:85], v[170:173], v[194:197], v[82:85]
	v_mfma_f32_16x16x32_bf16 v[70:73], v[162:165], v[202:205], v[70:73]
	v_mfma_f32_16x16x32_bf16 v[66:69], v[170:173], v[202:205], v[66:69]
	v_mfma_f32_16x16x32_bf16 v[118:121], v[166:169], v[182:185], v[118:121]
	v_mfma_f32_16x16x32_bf16 v[114:117], v[174:177], v[182:185], v[114:117]
	v_mfma_f32_16x16x32_bf16 v[102:105], v[166:169], v[190:193], v[102:105]
	v_mfma_f32_16x16x32_bf16 v[98:101], v[174:177], v[190:193], v[98:101]
	v_mfma_f32_16x16x32_bf16 v[86:89], v[166:169], v[198:201], v[86:89]
	v_mfma_f32_16x16x32_bf16 v[82:85], v[174:177], v[198:201], v[82:85]
	v_mfma_f32_16x16x32_bf16 v[70:73], v[166:169], v[206:209], v[70:73]
	v_mfma_f32_16x16x32_bf16 v[66:69], v[174:177], v[206:209], v[66:69]
	s_barrier
; #define PG8_STAGE(bufoff, gbase, voff) do { _Pragma("unroll") for (int _i = 0; _i < 2; ++_i) \
;         __builtin_amdgcn_global_load_lds((const unsigned*)((const char*)(gbase) + (voff)[_i]), (PG8_LAS unsigned*)(lds + (bufoff) + ldsw + _i * 8192), 16, 0, 0); } while (0)
; #define PG8_LDA(dst, b, h) do { _Pragma("unroll") for (int m = 0; m < 4; ++m) _Pragma("unroll") for (int k = 0; k < 2; ++k) dst[m][k] = *(const PG8_LAS bf16x8*)(lds + PG8_SA(b, h) + aoff + m * 2048 + k * 1024); } while (0)
; #define PG8_MMA(ai, bj, At, Bt) do { __builtin_amdgcn_s_setprio(1); _Pragma("unroll") for (int m = 0; m < 4; ++m) _Pragma("unroll") for (int n = 0; n < 2; ++n) _Pragma("unroll") for (int k = 0; k < 2; ++k) \
;         acc[ai][bj][m][n] = __builtin_amdgcn_mfma_f32_16x16x32_bf16(Bt[n][k], At[m][k], acc[ai][bj][m][n], 0, 0, 0); __builtin_amdgcn_s_setprio(0); } while (0)
; #define PG8_WAIT_V(n) asm volatile("s_waitcnt vmcnt(" #n ")" ::: "memory")
; #define PG8_WAIT_L(n) asm volatile("s_waitcnt lgkmcnt(" #n ")" ::: "memory")
; #define PG8_BAR __builtin_amdgcn_s_barrier()
; #define PG8_SCHED __builtin_amdgcn_sched_barrier(0)
; template <class Epi, class Sched, bool ALIGN_EPI = false, bool SP2 = false>
; __device__ __forceinline__ void gemm_phase(PG8_LAS unsigned char* lds, const Gemm g, const Sched& S, const Epi& E, int wave_s) {
;     ...
;         for (int t = 0; t < nt; t += 2) {
;             const bool last = (t == nt - 2);
;             const char* a1 = cA + (size_t)(t + 1) * kstep;
;             const char* a2 = last ? nA : cA + (size_t)(t + 2) * kstep; const char* b2 = last ? nB : cB + (size_t)(t + 2) * kstep;
;     ...
;             PG8_LDA(At, 1, 1); PG8_STAGE(PG8_SB(1, 0), b3, voffB); PG8_STAGE(PG8_SB(1, 1), b3 + hstepB, voffB); PG8_STAGE(PG8_SA(1, 0), a3, voffA);
;             PG8_WAIT_V(8); PG8_WAIT_L(0); PG8_BAR; PG8_MMA(1, 0, At, B0); PG8_MMA(1, 1, At, B1); PG8_BAR; PG8_SCHED;
	s_add_i32 s40, s95, s34
	v_lshl_add_u64 v[210:211], v[210:211], 0, s[60:61]
	s_mov_b32 m0, s40
	ds_read_b128 v[178:181], v148 offset:49152
	ds_read_b128 v[182:185], v148 offset:50176
	ds_read_b128 v[186:189], v148 offset:51200
	ds_read_b128 v[190:193], v148 offset:52224
	ds_read_b128 v[194:197], v148 offset:53248
	ds_read_b128 v[198:201], v148 offset:54272
	ds_read_b128 v[202:205], v148 offset:55296
	ds_read_b128 v[206:209], v148 offset:56320
	global_load_lds_dwordx4 v[210:211], off
	s_add_i32 m0, s40, 0x2000
	s_add_u32 s30, s30, 0x80080
	v_lshl_add_u64 v[210:211], v[212:213], 0, s[60:61]
	s_addc_u32 s31, s31, 0
	s_add_i32 s40, s96, s34
	global_load_lds_dwordx4 v[210:211], off
	v_lshl_add_u64 v[210:211], s[30:31], 0, v[132:133]
	s_mov_b32 m0, s40
	s_nop 0
	global_load_lds_dwordx4 v[210:211], off
	v_lshl_add_u64 v[210:211], s[30:31], 0, v[136:137]
	s_add_i32 m0, s40, 0x2000
	s_nop 0
	global_load_lds_dwordx4 v[210:211], off
	v_lshl_add_u64 v[210:211], v[214:215], 0, s[60:61]
	s_mov_b32 m0, s45
	s_nop 0
	global_load_lds_dwordx4 v[210:211], off
	v_lshl_add_u64 v[210:211], v[216:217], 0, s[60:61]
	s_mov_b32 m0, s46
	s_nop 0
	global_load_lds_dwordx4 v[210:211], off
	s_waitcnt vmcnt(8)
	s_waitcnt lgkmcnt(0)
	s_barrier
	s_waitcnt lgkmcnt(0)
	v_mfma_f32_16x16x32_bf16 v[62:65], v[142:145], v[178:181], v[62:65]
	v_mfma_f32_16x16x32_bf16 v[58:61], v[154:157], v[178:181], v[58:61]
	v_mfma_f32_16x16x32_bf16 v[46:49], v[142:145], v[186:189], v[46:49]
	v_mfma_f32_16x16x32_bf16 v[42:45], v[154:157], v[186:189], v[42:45]
	v_mfma_f32_16x16x32_bf16 v[30:33], v[142:145], v[194:197], v[30:33]
	v_mfma_f32_16x16x32_bf16 v[26:29], v[154:157], v[194:197], v[26:29]
	v_mfma_f32_16x16x32_bf16 v[14:17], v[142:145], v[202:205], v[14:17]
	v_mfma_f32_16x16x32_bf16 v[10:13], v[154:157], v[202:205], v[10:13]
	v_mfma_f32_16x16x32_bf16 v[62:65], v[150:153], v[182:185], v[62:65]
	v_mfma_f32_16x16x32_bf16 v[58:61], v[158:161], v[182:185], v[58:61]
	v_mfma_f32_16x16x32_bf16 v[46:49], v[150:153], v[190:193], v[46:49]
	v_mfma_f32_16x16x32_bf16 v[42:45], v[158:161], v[190:193], v[42:45]
	v_mfma_f32_16x16x32_bf16 v[30:33], v[150:153], v[198:201], v[30:33]
	v_mfma_f32_16x16x32_bf16 v[26:29], v[158:161], v[198:201], v[26:29]
	v_mfma_f32_16x16x32_bf16 v[14:17], v[150:153], v[206:209], v[14:17]
	v_mfma_f32_16x16x32_bf16 v[10:13], v[158:161], v[206:209], v[10:13]
	v_mfma_f32_16x16x32_bf16 v[54:57], v[162:165], v[178:181], v[54:57]
	v_mfma_f32_16x16x32_bf16 v[50:53], v[170:173], v[178:181], v[50:53]
	v_mfma_f32_16x16x32_bf16 v[38:41], v[162:165], v[186:189], v[38:41]
	v_mfma_f32_16x16x32_bf16 v[34:37], v[170:173], v[186:189], v[34:37]
	v_mfma_f32_16x16x32_bf16 v[22:25], v[162:165], v[194:197], v[22:25]
	v_mfma_f32_16x16x32_bf16 v[18:21], v[170:173], v[194:197], v[18:21]
	v_mfma_f32_16x16x32_bf16 v[6:9], v[162:165], v[202:205], v[6:9]
	v_mfma_f32_16x16x32_bf16 v[2:5], v[170:173], v[202:205], v[2:5]
	v_mfma_f32_16x16x32_bf16 v[54:57], v[166:169], v[182:185], v[54:57]
	v_mfma_f32_16x16x32_bf16 v[50:53], v[174:177], v[182:185], v[50:53]
	v_mfma_f32_16x16x32_bf16 v[38:41], v[166:169], v[190:193], v[38:41]
	v_mfma_f32_16x16x32_bf16 v[34:37], v[174:177], v[190:193], v[34:37]
	v_mfma_f32_16x16x32_bf16 v[22:25], v[166:169], v[198:201], v[22:25]
	v_mfma_f32_16x16x32_bf16 v[18:21], v[174:177], v[198:201], v[18:21]
	v_mfma_f32_16x16x32_bf16 v[6:9], v[166:169], v[206:209], v[6:9]
	v_mfma_f32_16x16x32_bf16 v[2:5], v[174:177], v[206:209], v[2:5]
	s_barrier
	s_add_i32 s94, s94, 2
	s_add_u32 s4, s4, 0x100
	s_addc_u32 s5, s5, 0
	s_add_u32 s15, s15, 0x100
	s_addc_u32 s21, s21, 0
	s_cmp_gt_u32 s94, 29
	s_cbranch_scc0 .LBB0_412
	s_and_b64 vcc, exec, s[12:13]
	s_cbranch_vccz .LBB0_415
	s_barrier

; #define PG8_STAGE(bufoff, gbase, voff) do { _Pragma("unroll") for (int _i = 0; _i < 2; ++_i) \
;         __builtin_amdgcn_global_load_lds((const unsigned*)((const char*)(gbase) + (voff)[_i]), (PG8_LAS unsigned*)(lds + (bufoff) + ldsw + _i * 8192), 16, 0, 0); } while (0)
; #define PG8_LDA(dst, b, h) do { _Pragma("unroll") for (int m = 0; m < 4; ++m) _Pragma("unroll") for (int k = 0; k < 2; ++k) dst[m][k] = *(const PG8_LAS bf16x8*)(lds + PG8_SA(b, h) + aoff + m * 2048 + k * 1024); } while (0)
; #define PG8_LDB(dst, b, h) do { _Pragma("unroll") for (int n = 0; n < 2; ++n) _Pragma("unroll") for (int k = 0; k < 2; ++k) dst[n][k] = *(const PG8_LAS bf16x8*)(lds + PG8_SB(b, h) + boff + n * 2048 + k * 1024); } while (0)
; #define PG8_MMA(ai, bj, At, Bt) do { __builtin_amdgcn_s_setprio(1); _Pragma("unroll") for (int m = 0; m < 4; ++m) _Pragma("unroll") for (int n = 0; n < 2; ++n) _Pragma("unroll") for (int k = 0; k < 2; ++k) \
;         acc[ai][bj][m][n] = __builtin_amdgcn_mfma_f32_16x16x32_bf16(Bt[n][k], At[m][k], acc[ai][bj][m][n], 0, 0, 0); __builtin_amdgcn_s_setprio(0); } while (0)
; #define PG8_WAIT_V(n) asm volatile("s_waitcnt vmcnt(" #n ")" ::: "memory")
; #define PG8_WAIT_L(n) asm volatile("s_waitcnt lgkmcnt(" #n ")" ::: "memory")
; #define PG8_BAR __builtin_amdgcn_s_barrier()
; #define PG8_SCHED __builtin_amdgcn_sched_barrier(0)
; template <class Epi, class Sched, bool ALIGN_EPI = false, bool SP2 = false>
; __device__ __forceinline__ void gemm_phase(PG8_LAS unsigned char* lds, const Gemm g, const Sched& S, const Epi& E, int wave_s) {
;     ...
;             PG8_LDB(B0, 0, 0); PG8_LDB(B1, 0, 1); PG8_SCHED; PG8_LDA(At, 0, 0); PG8_STAGE(PG8_SA(1, 1), a1 + hstepA, voffA);
;             PG8_WAIT_V(8); PG8_WAIT_L(0); PG8_BAR; PG8_MMA(0, 0, At, B0); PG8_MMA(0, 1, At, B1); PG8_BAR; PG8_SCHED;
;             PG8_LDA(At, 0, 1); PG8_STAGE(PG8_SB(0, 0), b2, voffB); PG8_STAGE(PG8_SB(0, 1), b2 + hstepB, voffB); PG8_STAGE(PG8_SA(0, 0), a2, voffA);
;             PG8_WAIT_V(8); PG8_WAIT_L(0); PG8_BAR; PG8_MMA(1, 0, At, B0); PG8_MMA(1, 1, At, B1); PG8_BAR; PG8_SCHED;
.LBB0_602:
	s_add_i32 s84, 0, 0x10000
	s_add_i32 s90, 0, 0x14000
	v_add_u32_e32 v134, s84, v207
	v_add_u32_e32 v158, s90, v207
	ds_read_b128 v[118:121], v134
	ds_read_b128 v[126:129], v134 offset:1024
	ds_read_b128 v[130:133], v134 offset:2048
	ds_read_b128 v[134:137], v134 offset:3072
	ds_read_b128 v[138:141], v158
	ds_read_b128 v[142:145], v158 offset:1024
	ds_read_b128 v[154:157], v158 offset:2048
	ds_read_b128 v[158:161], v158 offset:3072
	s_add_u32 s30, s4, 0xfff80080
	s_addc_u32 s31, s5, -1
	s_cmp_eq_u32 s81, 28
	s_cselect_b32 s41, s29, s31
	s_cselect_b32 s40, s28, s30
	s_cselect_b32 s31, s2, s27
	s_cselect_b32 s30, s3, s21
	v_lshl_add_u64 v[210:211], s[4:5], 0, v[198:199]
	s_add_i32 m0, s35, 0xc000
	ds_read_b128 v[162:165], v208
	ds_read_b128 v[166:169], v208 offset:1024
	ds_read_b128 v[170:173], v208 offset:2048
	ds_read_b128 v[174:177], v208 offset:3072
	ds_read_b128 v[178:181], v208 offset:4096
	ds_read_b128 v[182:185], v208 offset:5120
	ds_read_b128 v[186:189], v208 offset:6144
	ds_read_b128 v[202:205], v208 offset:7168
	global_load_lds_dwordx4 v[210:211], off
	v_lshl_add_u64 v[210:211], s[4:5], 0, v[200:201]
	s_add_i32 m0, s35, 0xe000
	s_nop 0
	global_load_lds_dwordx4 v[210:211], off
	s_waitcnt vmcnt(8)
	s_waitcnt lgkmcnt(0)
	s_barrier
	s_waitcnt lgkmcnt(0)
	v_mfma_f32_16x16x32_bf16 v[150:153], v[118:121], v[162:165], v[150:153]
	v_mfma_f32_16x16x32_bf16 v[146:149], v[130:133], v[162:165], v[146:149]
	v_mfma_f32_16x16x32_bf16 v[110:113], v[118:121], v[170:173], v[110:113]
	v_mfma_f32_16x16x32_bf16 v[106:109], v[130:133], v[170:173], v[106:109]
	v_mfma_f32_16x16x32_bf16 v[94:97], v[118:121], v[178:181], v[94:97]
	v_mfma_f32_16x16x32_bf16 v[90:93], v[130:133], v[178:181], v[90:93]
	v_mfma_f32_16x16x32_bf16 v[78:81], v[118:121], v[186:189], v[78:81]
	v_mfma_f32_16x16x32_bf16 v[74:77], v[130:133], v[186:189], v[74:77]
	v_mfma_f32_16x16x32_bf16 v[150:153], v[126:129], v[166:169], v[150:153]
	v_mfma_f32_16x16x32_bf16 v[146:149], v[134:137], v[166:169], v[146:149]
	v_mfma_f32_16x16x32_bf16 v[110:113], v[126:129], v[174:177], v[110:113]
	v_mfma_f32_16x16x32_bf16 v[106:109], v[134:137], v[174:177], v[106:109]
	v_mfma_f32_16x16x32_bf16 v[94:97], v[126:129], v[182:185], v[94:97]
	v_mfma_f32_16x16x32_bf16 v[90:93], v[134:137], v[182:185], v[90:93]
	v_mfma_f32_16x16x32_bf16 v[78:81], v[126:129], v[202:205], v[78:81]
	v_mfma_f32_16x16x32_bf16 v[74:77], v[134:137], v[202:205], v[74:77]
	v_mfma_f32_16x16x32_bf16 v[122:125], v[138:141], v[162:165], v[122:125]
	v_mfma_f32_16x16x32_bf16 v[114:117], v[154:157], v[162:165], v[114:117]
	v_mfma_f32_16x16x32_bf16 v[102:105], v[138:141], v[170:173], v[102:105]
	v_mfma_f32_16x16x32_bf16 v[98:101], v[154:157], v[170:173], v[98:101]
	v_mfma_f32_16x16x32_bf16 v[86:89], v[138:141], v[178:181], v[86:89]
	v_mfma_f32_16x16x32_bf16 v[82:85], v[154:157], v[178:181], v[82:85]
	v_mfma_f32_16x16x32_bf16 v[70:73], v[138:141], v[186:189], v[70:73]
	v_mfma_f32_16x16x32_bf16 v[66:69], v[154:157], v[186:189], v[66:69]
	v_mfma_f32_16x16x32_bf16 v[122:125], v[142:145], v[166:169], v[122:125]
	v_mfma_f32_16x16x32_bf16 v[114:117], v[158:161], v[166:169], v[114:117]
	v_mfma_f32_16x16x32_bf16 v[102:105], v[142:145], v[174:177], v[102:105]
	v_mfma_f32_16x16x32_bf16 v[98:101], v[158:161], v[174:177], v[98:101]
	v_mfma_f32_16x16x32_bf16 v[86:89], v[142:145], v[182:185], v[86:89]
	v_mfma_f32_16x16x32_bf16 v[82:85], v[158:161], v[182:185], v[82:85]
	v_mfma_f32_16x16x32_bf16 v[70:73], v[142:145], v[202:205], v[70:73]
	v_mfma_f32_16x16x32_bf16 v[66:69], v[158:161], v[202:205], v[66:69]
	s_barrier
	s_add_i32 s84, s84, s34
	v_lshl_add_u64 v[210:211], s[30:31], 0, v[194:195]
	s_mov_b32 m0, s84
	ds_read_b128 v[162:165], v208 offset:16384
	ds_read_b128 v[166:169], v208 offset:17408
	ds_read_b128 v[170:173], v208 offset:18432
	ds_read_b128 v[174:177], v208 offset:19456
	ds_read_b128 v[178:181], v208 offset:20480
	ds_read_b128 v[182:185], v208 offset:21504
	ds_read_b128 v[186:189], v208 offset:22528
	ds_read_b128 v[202:205], v208 offset:23552
	global_load_lds_dwordx4 v[210:211], off
	s_add_i32 m0, s84, 0x2000
	s_add_u32 s84, s30, 0x80000
	v_lshl_add_u64 v[212:213], s[30:31], 0, v[190:191]
	s_addc_u32 s85, s31, 0
	s_add_i32 s90, s90, s34
	global_load_lds_dwordx4 v[212:213], off
	v_lshl_add_u64 v[214:215], s[84:85], 0, v[194:195]
	s_mov_b32 m0, s90
	v_lshl_add_u64 v[216:217], s[40:41], 0, v[192:193]
	global_load_lds_dwordx4 v[214:215], off
	v_lshl_add_u64 v[214:215], s[84:85], 0, v[190:191]
	s_add_i32 m0, s90, 0x2000
	s_nop 0
	global_load_lds_dwordx4 v[214:215], off
	v_lshl_add_u64 v[214:215], s[40:41], 0, v[196:197]
	s_mov_b32 m0, s35
	s_nop 0
	global_load_lds_dwordx4 v[214:215], off
	s_mov_b32 m0, s36
	s_nop 0
	global_load_lds_dwordx4 v[216:217], off
	s_waitcnt vmcnt(8)
	s_waitcnt lgkmcnt(0)
	s_barrier
; #define PG8_STAGE(bufoff, gbase, voff) do { _Pragma("unroll") for (int _i = 0; _i < 2; ++_i) \
;         __builtin_amdgcn_global_load_lds((const unsigned*)((const char*)(gbase) + (voff)[_i]), (PG8_LAS unsigned*)(lds + (bufoff) + ldsw + _i * 8192), 16, 0, 0); } while (0)
; #define PG8_LDA(dst, b, h) do { _Pragma("unroll") for (int m = 0; m < 4; ++m) _Pragma("unroll") for (int k = 0; k < 2; ++k) dst[m][k] = *(const PG8_LAS bf16x8*)(lds + PG8_SA(b, h) + aoff + m * 2048 + k * 1024); } while (0)
; #define PG8_LDB(dst, b, h) do { _Pragma("unroll") for (int n = 0; n < 2; ++n) _Pragma("unroll") for (int k = 0; k < 2; ++k) dst[n][k] = *(const PG8_LAS bf16x8*)(lds + PG8_SB(b, h) + boff + n * 2048 + k * 1024); } while (0)
; #define PG8_MMA(ai, bj, At, Bt) do { __builtin_amdgcn_s_setprio(1); _Pragma("unroll") for (int m = 0; m < 4; ++m) _Pragma("unroll") for (int n = 0; n < 2; ++n) _Pragma("unroll") for (int k = 0; k < 2; ++k) \
;         acc[ai][bj][m][n] = __builtin_amdgcn_mfma_f32_16x16x32_bf16(Bt[n][k], At[m][k], acc[ai][bj][m][n], 0, 0, 0); __builtin_amdgcn_s_setprio(0); } while (0)
; #define PG8_WAIT_V(n) asm volatile("s_waitcnt vmcnt(" #n ")" ::: "memory")
; #define PG8_WAIT_L(n) asm volatile("s_waitcnt lgkmcnt(" #n ")" ::: "memory")
; #define PG8_BAR __builtin_amdgcn_s_barrier()
; #define PG8_SCHED __builtin_amdgcn_sched_barrier(0)
; template <class Epi, class Sched, bool ALIGN_EPI = false, bool SP2 = false>
; __device__ __forceinline__ void gemm_phase(PG8_LAS unsigned char* lds, const Gemm g, const Sched& S, const Epi& E, int wave_s) {
;     ...
;             PG8_WAIT_V(8); PG8_WAIT_L(0); PG8_BAR; PG8_MMA(1, 0, At, B0); PG8_MMA(1, 1, At, B1); PG8_BAR; PG8_SCHED;
;             PG8_LDB(B0, 1, 0); PG8_LDB(B1, 1, 1); PG8_SCHED; PG8_LDA(At, 1, 0); PG8_STAGE(PG8_SA(0, 1), a2 + hstepA, voffA);
;             PG8_WAIT_V(8); PG8_WAIT_L(0); PG8_BAR; PG8_MMA(0, 0, At, B0); PG8_MMA(0, 1, At, B1); PG8_BAR; PG8_SCHED;
	s_waitcnt lgkmcnt(0)
	v_mfma_f32_16x16x32_bf16 v[62:65], v[118:121], v[162:165], v[62:65]
	v_mfma_f32_16x16x32_bf16 v[58:61], v[130:133], v[162:165], v[58:61]
	v_mfma_f32_16x16x32_bf16 v[46:49], v[118:121], v[170:173], v[46:49]
	v_mfma_f32_16x16x32_bf16 v[42:45], v[130:133], v[170:173], v[42:45]
	v_mfma_f32_16x16x32_bf16 v[30:33], v[118:121], v[178:181], v[30:33]
	v_mfma_f32_16x16x32_bf16 v[26:29], v[130:133], v[178:181], v[26:29]
	v_mfma_f32_16x16x32_bf16 v[14:17], v[118:121], v[186:189], v[14:17]
	v_mfma_f32_16x16x32_bf16 v[10:13], v[130:133], v[186:189], v[10:13]
	v_mfma_f32_16x16x32_bf16 v[62:65], v[126:129], v[166:169], v[62:65]
	v_mfma_f32_16x16x32_bf16 v[58:61], v[134:137], v[166:169], v[58:61]
	v_mfma_f32_16x16x32_bf16 v[46:49], v[126:129], v[174:177], v[46:49]
	v_mfma_f32_16x16x32_bf16 v[42:45], v[134:137], v[174:177], v[42:45]
	v_mfma_f32_16x16x32_bf16 v[30:33], v[126:129], v[182:185], v[30:33]
	v_mfma_f32_16x16x32_bf16 v[26:29], v[134:137], v[182:185], v[26:29]
	v_mfma_f32_16x16x32_bf16 v[14:17], v[126:129], v[202:205], v[14:17]
	v_mfma_f32_16x16x32_bf16 v[10:13], v[134:137], v[202:205], v[10:13]
	v_mfma_f32_16x16x32_bf16 v[54:57], v[138:141], v[162:165], v[54:57]
	v_mfma_f32_16x16x32_bf16 v[50:53], v[154:157], v[162:165], v[50:53]
	v_mfma_f32_16x16x32_bf16 v[38:41], v[138:141], v[170:173], v[38:41]
	v_mfma_f32_16x16x32_bf16 v[34:37], v[154:157], v[170:173], v[34:37]
	v_mfma_f32_16x16x32_bf16 v[22:25], v[138:141], v[178:181], v[22:25]
	v_mfma_f32_16x16x32_bf16 v[18:21], v[154:157], v[178:181], v[18:21]
	v_mfma_f32_16x16x32_bf16 v[6:9], v[138:141], v[186:189], v[6:9]
	v_mfma_f32_16x16x32_bf16 v[2:5], v[154:157], v[186:189], v[2:5]
	v_mfma_f32_16x16x32_bf16 v[54:57], v[142:145], v[166:169], v[54:57]
	v_mfma_f32_16x16x32_bf16 v[50:53], v[158:161], v[166:169], v[50:53]
	v_mfma_f32_16x16x32_bf16 v[38:41], v[142:145], v[174:177], v[38:41]
	v_mfma_f32_16x16x32_bf16 v[34:37], v[158:161], v[174:177], v[34:37]
	v_mfma_f32_16x16x32_bf16 v[22:25], v[142:145], v[182:185], v[22:25]
	v_mfma_f32_16x16x32_bf16 v[18:21], v[158:161], v[182:185], v[18:21]
	v_mfma_f32_16x16x32_bf16 v[6:9], v[142:145], v[202:205], v[6:9]
	v_mfma_f32_16x16x32_bf16 v[2:5], v[158:161], v[202:205], v[2:5]
	s_barrier
	s_add_i32 s84, 0, 0x18000
	s_add_i32 s85, 0, 0x1c000
	v_add_u32_e32 v134, s84, v207
	v_add_u32_e32 v158, s85, v207
	ds_read_b128 v[118:121], v134
	ds_read_b128 v[126:129], v134 offset:1024
	ds_read_b128 v[130:133], v134 offset:2048
	ds_read_b128 v[134:137], v134 offset:3072
	ds_read_b128 v[138:141], v158
	ds_read_b128 v[142:145], v158 offset:1024
	ds_read_b128 v[154:157], v158 offset:2048
	ds_read_b128 v[158:161], v158 offset:3072
	s_add_u32 s40, s40, 0x80000
	s_addc_u32 s41, s41, 0
	s_mov_b32 m0, s37
	v_lshl_add_u64 v[218:219], s[40:41], 0, v[196:197]
	ds_read_b128 v[162:165], v208 offset:32768
	ds_read_b128 v[166:169], v208 offset:33792
	ds_read_b128 v[170:173], v208 offset:34816
	ds_read_b128 v[174:177], v208 offset:35840
	ds_read_b128 v[178:181], v208 offset:36864
	ds_read_b128 v[182:185], v208 offset:37888
	ds_read_b128 v[186:189], v208 offset:38912
	ds_read_b128 v[202:205], v208 offset:39936
	global_load_lds_dwordx4 v[218:219], off
	v_lshl_add_u64 v[218:219], s[40:41], 0, v[192:193]
	s_mov_b32 m0, s42
	s_nop 0
	global_load_lds_dwordx4 v[218:219], off
	s_waitcnt vmcnt(8)
	s_waitcnt lgkmcnt(0)
	s_barrier
	s_waitcnt lgkmcnt(0)
	v_mfma_f32_16x16x32_bf16 v[150:153], v[118:121], v[162:165], v[150:153]
	v_mfma_f32_16x16x32_bf16 v[146:149], v[130:133], v[162:165], v[146:149]
	v_mfma_f32_16x16x32_bf16 v[110:113], v[118:121], v[170:173], v[110:113]
	v_mfma_f32_16x16x32_bf16 v[106:109], v[130:133], v[170:173], v[106:109]
	v_mfma_f32_16x16x32_bf16 v[94:97], v[118:121], v[178:181], v[94:97]
	v_mfma_f32_16x16x32_bf16 v[90:93], v[130:133], v[178:181], v[90:93]
	v_mfma_f32_16x16x32_bf16 v[78:81], v[118:121], v[186:189], v[78:81]
	v_mfma_f32_16x16x32_bf16 v[74:77], v[130:133], v[186:189], v[74:77]
	v_mfma_f32_16x16x32_bf16 v[150:153], v[126:129], v[166:169], v[150:153]
	v_mfma_f32_16x16x32_bf16 v[146:149], v[134:137], v[166:169], v[146:149]
	v_mfma_f32_16x16x32_bf16 v[110:113], v[126:129], v[174:177], v[110:113]
	v_mfma_f32_16x16x32_bf16 v[106:109], v[134:137], v[174:177], v[106:109]
	v_mfma_f32_16x16x32_bf16 v[94:97], v[126:129], v[182:185], v[94:97]
	v_mfma_f32_16x16x32_bf16 v[90:93], v[134:137], v[182:185], v[90:93]
	v_mfma_f32_16x16x32_bf16 v[78:81], v[126:129], v[202:205], v[78:81]
	v_mfma_f32_16x16x32_bf16 v[74:77], v[134:137], v[202:205], v[74:77]
	v_mfma_f32_16x16x32_bf16 v[122:125], v[138:141], v[162:165], v[122:125]
	v_mfma_f32_16x16x32_bf16 v[114:117], v[154:157], v[162:165], v[114:117]
	v_mfma_f32_16x16x32_bf16 v[102:105], v[138:141], v[170:173], v[102:105]
	v_mfma_f32_16x16x32_bf16 v[98:101], v[154:157], v[170:173], v[98:101]
	v_mfma_f32_16x16x32_bf16 v[86:89], v[138:141], v[178:181], v[86:89]
	v_mfma_f32_16x16x32_bf16 v[82:85], v[154:157], v[178:181], v[82:85]
	v_mfma_f32_16x16x32_bf16 v[70:73], v[138:141], v[186:189], v[70:73]
	v_mfma_f32_16x16x32_bf16 v[66:69], v[154:157], v[186:189], v[66:69]
	v_mfma_f32_16x16x32_bf16 v[122:125], v[142:145], v[166:169], v[122:125]
	v_mfma_f32_16x16x32_bf16 v[114:117], v[158:161], v[166:169], v[114:117]
	v_mfma_f32_16x16x32_bf16 v[102:105], v[142:145], v[174:177], v[102:105]
	v_mfma_f32_16x16x32_bf16 v[98:101], v[158:161], v[174:177], v[98:101]
	v_mfma_f32_16x16x32_bf16 v[86:89], v[142:145], v[182:185], v[86:89]
	v_mfma_f32_16x16x32_bf16 v[82:85], v[158:161], v[182:185], v[82:85]
	v_mfma_f32_16x16x32_bf16 v[70:73], v[142:145], v[202:205], v[70:73]
	v_mfma_f32_16x16x32_bf16 v[66:69], v[158:161], v[202:205], v[66:69]
	s_barrier
; #define PG8_STAGE(bufoff, gbase, voff) do { _Pragma("unroll") for (int _i = 0; _i < 2; ++_i) \
;         __builtin_amdgcn_global_load_lds((const unsigned*)((const char*)(gbase) + (voff)[_i]), (PG8_LAS unsigned*)(lds + (bufoff) + ldsw + _i * 8192), 16, 0, 0); } while (0)
; #define PG8_LDA(dst, b, h) do { _Pragma("unroll") for (int m = 0; m < 4; ++m) _Pragma("unroll") for (int k = 0; k < 2; ++k) dst[m][k] = *(const PG8_LAS bf16x8*)(lds + PG8_SA(b, h) + aoff + m * 2048 + k * 1024); } while (0)
; #define PG8_MMA(ai, bj, At, Bt) do { __builtin_amdgcn_s_setprio(1); _Pragma("unroll") for (int m = 0; m < 4; ++m) _Pragma("unroll") for (int n = 0; n < 2; ++n) _Pragma("unroll") for (int k = 0; k < 2; ++k) \
;         acc[ai][bj][m][n] = __builtin_amdgcn_mfma_f32_16x16x32_bf16(Bt[n][k], At[m][k], acc[ai][bj][m][n], 0, 0, 0); __builtin_amdgcn_s_setprio(0); } while (0)
; #define PG8_WAIT_V(n) asm volatile("s_waitcnt vmcnt(" #n ")" ::: "memory")
; #define PG8_WAIT_L(n) asm volatile("s_waitcnt lgkmcnt(" #n ")" ::: "memory")
; #define PG8_BAR __builtin_amdgcn_s_barrier()
; #define PG8_SCHED __builtin_amdgcn_sched_barrier(0)
; template <class Epi, class Sched, bool ALIGN_EPI = false, bool SP2 = false>
; __device__ __forceinline__ void gemm_phase(PG8_LAS unsigned char* lds, const Gemm g, const Sched& S, const Epi& E, int wave_s) {
;     ...
;         for (int t = 0; t < nt; t += 2) {
;             const bool last = (t == nt - 2);
;     ...
;             PG8_LDA(At, 1, 1); PG8_STAGE(PG8_SB(1, 0), b3, voffB); PG8_STAGE(PG8_SB(1, 1), b3 + hstepB, voffB); PG8_STAGE(PG8_SA(1, 0), a3, voffA);
;             PG8_WAIT_V(8); PG8_WAIT_L(0); PG8_BAR; PG8_MMA(1, 0, At, B0); PG8_MMA(1, 1, At, B1); PG8_BAR; PG8_SCHED;
	s_add_i32 s40, s84, s34
	v_lshl_add_u64 v[210:211], v[210:211], 0, s[60:61]
	s_mov_b32 m0, s40
	ds_read_b128 v[162:165], v208 offset:49152
	ds_read_b128 v[166:169], v208 offset:50176
	ds_read_b128 v[170:173], v208 offset:51200
	ds_read_b128 v[174:177], v208 offset:52224
	ds_read_b128 v[178:181], v208 offset:53248
	ds_read_b128 v[182:185], v208 offset:54272
	ds_read_b128 v[186:189], v208 offset:55296
	ds_read_b128 v[202:205], v208 offset:56320
	global_load_lds_dwordx4 v[210:211], off
	s_add_i32 m0, s40, 0x2000
	s_add_u32 s30, s30, 0x80080
	v_lshl_add_u64 v[210:211], v[212:213], 0, s[60:61]
	s_addc_u32 s31, s31, 0
	s_add_i32 s40, s85, s34
	global_load_lds_dwordx4 v[210:211], off
	v_lshl_add_u64 v[210:211], s[30:31], 0, v[194:195]
	s_mov_b32 m0, s40
	s_nop 0
	global_load_lds_dwordx4 v[210:211], off
	v_lshl_add_u64 v[210:211], s[30:31], 0, v[190:191]
	s_add_i32 m0, s40, 0x2000
	s_nop 0
	global_load_lds_dwordx4 v[210:211], off
	v_lshl_add_u64 v[210:211], v[214:215], 0, s[60:61]
	s_mov_b32 m0, s46
	s_nop 0
	global_load_lds_dwordx4 v[210:211], off
	v_lshl_add_u64 v[210:211], v[216:217], 0, s[60:61]
	s_mov_b32 m0, s47
	s_nop 0
	global_load_lds_dwordx4 v[210:211], off
	s_waitcnt vmcnt(8)
	s_waitcnt lgkmcnt(0)
	s_barrier
	s_waitcnt lgkmcnt(0)
	v_mfma_f32_16x16x32_bf16 v[62:65], v[118:121], v[162:165], v[62:65]
	v_mfma_f32_16x16x32_bf16 v[58:61], v[130:133], v[162:165], v[58:61]
	v_mfma_f32_16x16x32_bf16 v[46:49], v[118:121], v[170:173], v[46:49]
	v_mfma_f32_16x16x32_bf16 v[42:45], v[130:133], v[170:173], v[42:45]
	v_mfma_f32_16x16x32_bf16 v[30:33], v[118:121], v[178:181], v[30:33]
	v_mfma_f32_16x16x32_bf16 v[26:29], v[130:133], v[178:181], v[26:29]
	v_mfma_f32_16x16x32_bf16 v[14:17], v[118:121], v[186:189], v[14:17]
	v_mfma_f32_16x16x32_bf16 v[10:13], v[130:133], v[186:189], v[10:13]
	v_mfma_f32_16x16x32_bf16 v[62:65], v[126:129], v[166:169], v[62:65]
	v_mfma_f32_16x16x32_bf16 v[58:61], v[134:137], v[166:169], v[58:61]
	v_mfma_f32_16x16x32_bf16 v[46:49], v[126:129], v[174:177], v[46:49]
	v_mfma_f32_16x16x32_bf16 v[42:45], v[134:137], v[174:177], v[42:45]
	v_mfma_f32_16x16x32_bf16 v[30:33], v[126:129], v[182:185], v[30:33]
	v_mfma_f32_16x16x32_bf16 v[26:29], v[134:137], v[182:185], v[26:29]
	v_mfma_f32_16x16x32_bf16 v[14:17], v[126:129], v[202:205], v[14:17]
	v_mfma_f32_16x16x32_bf16 v[10:13], v[134:137], v[202:205], v[10:13]
	v_mfma_f32_16x16x32_bf16 v[54:57], v[138:141], v[162:165], v[54:57]
	v_mfma_f32_16x16x32_bf16 v[50:53], v[154:157], v[162:165], v[50:53]
	v_mfma_f32_16x16x32_bf16 v[38:41], v[138:141], v[170:173], v[38:41]
	v_mfma_f32_16x16x32_bf16 v[34:37], v[154:157], v[170:173], v[34:37]
	v_mfma_f32_16x16x32_bf16 v[22:25], v[138:141], v[178:181], v[22:25]
	v_mfma_f32_16x16x32_bf16 v[18:21], v[154:157], v[178:181], v[18:21]
	v_mfma_f32_16x16x32_bf16 v[6:9], v[138:141], v[186:189], v[6:9]
	v_mfma_f32_16x16x32_bf16 v[2:5], v[154:157], v[186:189], v[2:5]
	v_mfma_f32_16x16x32_bf16 v[54:57], v[142:145], v[166:169], v[54:57]
	v_mfma_f32_16x16x32_bf16 v[50:53], v[158:161], v[166:169], v[50:53]
	v_mfma_f32_16x16x32_bf16 v[38:41], v[142:145], v[174:177], v[38:41]
	v_mfma_f32_16x16x32_bf16 v[34:37], v[158:161], v[174:177], v[34:37]
	v_mfma_f32_16x16x32_bf16 v[22:25], v[142:145], v[182:185], v[22:25]
	v_mfma_f32_16x16x32_bf16 v[18:21], v[158:161], v[182:185], v[18:21]
	v_mfma_f32_16x16x32_bf16 v[6:9], v[142:145], v[202:205], v[6:9]
	v_mfma_f32_16x16x32_bf16 v[2:5], v[158:161], v[202:205], v[2:5]
	s_barrier
	s_add_i32 s81, s81, 2
	s_add_u32 s4, s4, 0x100
	s_addc_u32 s5, s5, 0
	s_add_u32 s21, s21, 0x100
	s_addc_u32 s27, s27, 0
	s_cmp_gt_u32 s81, 29
	s_cbranch_scc0 .LBB0_602
	s_and_b64 vcc, exec, s[14:15]
	s_cbranch_vccz .LBB0_605
	s_barrier

; #define PG8_STAGE(bufoff, gbase, voff) do { _Pragma("unroll") for (int _i = 0; _i < 2; ++_i) \
;         __builtin_amdgcn_global_load_lds((const unsigned*)((const char*)(gbase) + (voff)[_i]), (PG8_LAS unsigned*)(lds + (bufoff) + ldsw + _i * 8192), 16, 0, 0); } while (0)
; #define PG8_LDA(dst, b, h) do { _Pragma("unroll") for (int m = 0; m < 4; ++m) _Pragma("unroll") for (int k = 0; k < 2; ++k) dst[m][k] = *(const PG8_LAS bf16x8*)(lds + PG8_SA(b, h) + aoff + m * 2048 + k * 1024); } while (0)
; #define PG8_LDB(dst, b, h) do { _Pragma("unroll") for (int n = 0; n < 2; ++n) _Pragma("unroll") for (int k = 0; k < 2; ++k) dst[n][k] = *(const PG8_LAS bf16x8*)(lds + PG8_SB(b, h) + boff + n * 2048 + k * 1024); } while (0)
; #define PG8_MMA(ai, bj, At, Bt) do { __builtin_amdgcn_s_setprio(1); _Pragma("unroll") for (int m = 0; m < 4; ++m) _Pragma("unroll") for (int n = 0; n < 2; ++n) _Pragma("unroll") for (int k = 0; k < 2; ++k) \
;         acc[ai][bj][m][n] = __builtin_amdgcn_mfma_f32_16x16x32_bf16(Bt[n][k], At[m][k], acc[ai][bj][m][n], 0, 0, 0); __builtin_amdgcn_s_setprio(0); } while (0)
; #define PG8_WAIT_V(n) asm volatile("s_waitcnt vmcnt(" #n ")" ::: "memory")
; #define PG8_WAIT_L(n) asm volatile("s_waitcnt lgkmcnt(" #n ")" ::: "memory")
; #define PG8_BAR __builtin_amdgcn_s_barrier()
; #define PG8_SCHED __builtin_amdgcn_sched_barrier(0)
; template <class Epi, class Sched, bool ALIGN_EPI = false, bool SP2 = false>
; __device__ __forceinline__ void gemm_phase(PG8_LAS unsigned char* lds, const Gemm g, const Sched& S, const Epi& E, int wave_s) {
;     ...
;             const bool last = (t == nt - 2);
;             const char* a1 = cA + (size_t)(t + 1) * kstep;
;             const char* a2 = last ? nA : cA + (size_t)(t + 2) * kstep; const char* b2 = last ? nB : cB + (size_t)(t + 2) * kstep;
;             const char* a3 = a2 + kstep; const char* b3 = b2 + kstep;
;             if (last && has_next) S.a_ready(nxt);
;             if constexpr (SP2) {
;             PG8_LDB(B0, 0, 0); PG8_LDB(B1, 0, 1); PG8_SCHED; PG8_LDA(At, 0, 0); PG8_STAGE(PG8_SA(1, 1), a1 + hstepA, voffA);
;             PG8_WAIT_V(8); PG8_WAIT_L(0); PG8_BAR; PG8_MMA(0, 0, At, B0); PG8_MMA(0, 1, At, B1); PG8_BAR; PG8_SCHED;
;             PG8_LDA(At, 0, 1); PG8_STAGE(PG8_SB(0, 0), b2, voffB); PG8_STAGE(PG8_SB(0, 1), b2 + hstepB, voffB); PG8_STAGE(PG8_SA(0, 0), a2, voffA);
.LBB0_691:
	s_add_i32 vcc_hi, 0, 0x10000
	s_add_i32 s86, 0, 0x14000
	v_add_u32_e32 v142, vcc_hi, v251
	v_add_u32_e32 v158, s86, v251
	ds_read_b128 v[126:129], v142
	ds_read_b128 v[134:137], v142 offset:1024
	ds_read_b128 v[138:141], v142 offset:2048
	ds_read_b128 v[142:145], v142 offset:3072
	ds_read_b128 v[146:149], v158
	ds_read_b128 v[150:153], v158 offset:1024
	ds_read_b128 v[154:157], v158 offset:2048
	ds_read_b128 v[158:161], v158 offset:3072
	s_add_u32 s4, s30, 0x100
	s_addc_u32 s5, s31, 0
	s_cmp_eq_u32 vcc_lo, 28
	s_cselect_b32 s41, s21, s5
	s_cselect_b32 s40, s20, s4
	s_cselect_b32 s7, s2, s91
	s_cselect_b32 s6, s3, s89
	v_lshl_add_u64 v[194:195], s[30:31], 0, v[244:245]
	s_add_i32 m0, s36, 0xc000
	ds_read_b128 v[162:165], v252
	ds_read_b128 v[166:169], v252 offset:1024
	ds_read_b128 v[170:173], v252 offset:2048
	ds_read_b128 v[174:177], v252 offset:3072
	ds_read_b128 v[178:181], v252 offset:4096
	ds_read_b128 v[182:185], v252 offset:5120
	ds_read_b128 v[186:189], v252 offset:6144
	ds_read_b128 v[190:193], v252 offset:7168
	global_load_lds_dwordx4 v[194:195], off
	v_lshl_add_u64 v[194:195], s[30:31], 0, v[246:247]
	s_add_i32 m0, s36, 0xe000
	s_nop 0
	global_load_lds_dwordx4 v[194:195], off
	s_waitcnt vmcnt(8)
	s_waitcnt lgkmcnt(0)
	s_barrier
	s_waitcnt lgkmcnt(0)
	v_mfma_f32_16x16x32_bf16 v[130:133], v[126:129], v[162:165], v[130:133]
	v_mfma_f32_16x16x32_bf16 v[118:121], v[138:141], v[162:165], v[118:121]
	v_mfma_f32_16x16x32_bf16 v[110:113], v[126:129], v[170:173], v[110:113]
	v_mfma_f32_16x16x32_bf16 v[98:101], v[138:141], v[170:173], v[98:101]
	v_mfma_f32_16x16x32_bf16 v[62:65], v[126:129], v[178:181], v[62:65]
	v_mfma_f32_16x16x32_bf16 v[58:61], v[138:141], v[178:181], v[58:61]
	v_mfma_f32_16x16x32_bf16 v[46:49], v[126:129], v[186:189], v[46:49]
	v_mfma_f32_16x16x32_bf16 v[42:45], v[138:141], v[186:189], v[42:45]
	v_mfma_f32_16x16x32_bf16 v[130:133], v[134:137], v[166:169], v[130:133]
	v_mfma_f32_16x16x32_bf16 v[118:121], v[142:145], v[166:169], v[118:121]
	v_mfma_f32_16x16x32_bf16 v[110:113], v[134:137], v[174:177], v[110:113]
	v_mfma_f32_16x16x32_bf16 v[98:101], v[142:145], v[174:177], v[98:101]
	v_mfma_f32_16x16x32_bf16 v[62:65], v[134:137], v[182:185], v[62:65]
	v_mfma_f32_16x16x32_bf16 v[58:61], v[142:145], v[182:185], v[58:61]
	v_mfma_f32_16x16x32_bf16 v[46:49], v[134:137], v[190:193], v[46:49]
	v_mfma_f32_16x16x32_bf16 v[42:45], v[142:145], v[190:193], v[42:45]
	v_mfma_f32_16x16x32_bf16 v[102:105], v[146:149], v[162:165], v[102:105]
	v_mfma_f32_16x16x32_bf16 v[74:77], v[154:157], v[162:165], v[74:77]
	v_mfma_f32_16x16x32_bf16 v[78:81], v[146:149], v[170:173], v[78:81]
	v_mfma_f32_16x16x32_bf16 v[90:93], v[154:157], v[170:173], v[90:93]
	v_mfma_f32_16x16x32_bf16 v[34:37], v[146:149], v[178:181], v[34:37]
	v_mfma_f32_16x16x32_bf16 v[26:29], v[154:157], v[178:181], v[26:29]
	v_mfma_f32_16x16x32_bf16 v[14:17], v[146:149], v[186:189], v[14:17]
	v_mfma_f32_16x16x32_bf16 v[2:5], v[154:157], v[186:189], v[2:5]
	v_mfma_f32_16x16x32_bf16 v[102:105], v[150:153], v[166:169], v[102:105]
	v_mfma_f32_16x16x32_bf16 v[74:77], v[158:161], v[166:169], v[74:77]
	v_mfma_f32_16x16x32_bf16 v[78:81], v[150:153], v[174:177], v[78:81]
	v_mfma_f32_16x16x32_bf16 v[90:93], v[158:161], v[174:177], v[90:93]
	v_mfma_f32_16x16x32_bf16 v[34:37], v[150:153], v[182:185], v[34:37]
	v_mfma_f32_16x16x32_bf16 v[26:29], v[158:161], v[182:185], v[26:29]
	v_mfma_f32_16x16x32_bf16 v[14:17], v[150:153], v[190:193], v[14:17]
	v_mfma_f32_16x16x32_bf16 v[2:5], v[158:161], v[190:193], v[2:5]
	s_barrier
	s_add_i32 s30, vcc_hi, s35
	v_lshl_add_u64 v[194:195], s[6:7], 0, v[238:239]
	s_mov_b32 m0, s30
	ds_read_b128 v[162:165], v252 offset:16384
	ds_read_b128 v[166:169], v252 offset:17408
	ds_read_b128 v[170:173], v252 offset:18432
	ds_read_b128 v[174:177], v252 offset:19456
	ds_read_b128 v[178:181], v252 offset:20480
	ds_read_b128 v[182:185], v252 offset:21504
	ds_read_b128 v[186:189], v252 offset:22528
	ds_read_b128 v[190:193], v252 offset:23552
	global_load_lds_dwordx4 v[194:195], off
	s_add_i32 m0, s30, 0x2000
	s_add_u32 s30, s6, 0x80000
	v_lshl_add_u64 v[196:197], s[6:7], 0, v[242:243]
	s_addc_u32 s31, s7, 0
	s_add_i32 s86, s86, s35
	global_load_lds_dwordx4 v[196:197], off
	v_lshl_add_u64 v[198:199], s[30:31], 0, v[238:239]
	s_mov_b32 m0, s86
	v_lshl_add_u64 v[200:201], s[40:41], 0, v[240:241]
	global_load_lds_dwordx4 v[198:199], off
	v_lshl_add_u64 v[198:199], s[30:31], 0, v[242:243]
	s_add_i32 m0, s86, 0x2000
	s_nop 0
	global_load_lds_dwordx4 v[198:199], off
	v_lshl_add_u64 v[198:199], s[40:41], 0, v[236:237]
	s_mov_b32 m0, s36
	s_nop 0
	global_load_lds_dwordx4 v[198:199], off
	s_mov_b32 m0, s37
	s_nop 0
	global_load_lds_dwordx4 v[200:201], off
	s_waitcnt vmcnt(8)
	s_waitcnt lgkmcnt(0)
	s_barrier
; #define PG8_STAGE(bufoff, gbase, voff) do { _Pragma("unroll") for (int _i = 0; _i < 2; ++_i) \
;         __builtin_amdgcn_global_load_lds((const unsigned*)((const char*)(gbase) + (voff)[_i]), (PG8_LAS unsigned*)(lds + (bufoff) + ldsw + _i * 8192), 16, 0, 0); } while (0)
; #define PG8_LDA(dst, b, h) do { _Pragma("unroll") for (int m = 0; m < 4; ++m) _Pragma("unroll") for (int k = 0; k < 2; ++k) dst[m][k] = *(const PG8_LAS bf16x8*)(lds + PG8_SA(b, h) + aoff + m * 2048 + k * 1024); } while (0)
; #define PG8_LDB(dst, b, h) do { _Pragma("unroll") for (int n = 0; n < 2; ++n) _Pragma("unroll") for (int k = 0; k < 2; ++k) dst[n][k] = *(const PG8_LAS bf16x8*)(lds + PG8_SB(b, h) + boff + n * 2048 + k * 1024); } while (0)
; #define PG8_MMA(ai, bj, At, Bt) do { __builtin_amdgcn_s_setprio(1); _Pragma("unroll") for (int m = 0; m < 4; ++m) _Pragma("unroll") for (int n = 0; n < 2; ++n) _Pragma("unroll") for (int k = 0; k < 2; ++k) \
;         acc[ai][bj][m][n] = __builtin_amdgcn_mfma_f32_16x16x32_bf16(Bt[n][k], At[m][k], acc[ai][bj][m][n], 0, 0, 0); __builtin_amdgcn_s_setprio(0); } while (0)
; #define PG8_WAIT_V(n) asm volatile("s_waitcnt vmcnt(" #n ")" ::: "memory")
; #define PG8_WAIT_L(n) asm volatile("s_waitcnt lgkmcnt(" #n ")" ::: "memory")
; #define PG8_BAR __builtin_amdgcn_s_barrier()
; #define PG8_SCHED __builtin_amdgcn_sched_barrier(0)
; template <class Epi, class Sched, bool ALIGN_EPI = false, bool SP2 = false>
; __device__ __forceinline__ void gemm_phase(PG8_LAS unsigned char* lds, const Gemm g, const Sched& S, const Epi& E, int wave_s) {
;     ...
;             PG8_WAIT_V(8); PG8_WAIT_L(0); PG8_BAR; PG8_MMA(1, 0, At, B0); PG8_MMA(1, 1, At, B1); PG8_BAR; PG8_SCHED;
;             PG8_LDB(B0, 1, 0); PG8_LDB(B1, 1, 1); PG8_SCHED; PG8_LDA(At, 1, 0); PG8_STAGE(PG8_SA(0, 1), a2 + hstepA, voffA);
;             PG8_WAIT_V(8); PG8_WAIT_L(0); PG8_BAR; PG8_MMA(0, 0, At, B0); PG8_MMA(0, 1, At, B1); PG8_BAR; PG8_SCHED;
	s_waitcnt lgkmcnt(0)
	v_mfma_f32_16x16x32_bf16 v[54:57], v[126:129], v[162:165], v[54:57]
	v_mfma_f32_16x16x32_bf16 v[50:53], v[138:141], v[162:165], v[50:53]
	v_mfma_f32_16x16x32_bf16 v[38:41], v[126:129], v[170:173], v[38:41]
	v_mfma_f32_16x16x32_bf16 v[30:33], v[138:141], v[170:173], v[30:33]
	v_mfma_f32_16x16x32_bf16 v[86:89], v[126:129], v[178:181], v[86:89]
	v_mfma_f32_16x16x32_bf16 v[122:125], v[138:141], v[178:181], v[122:125]
	v_mfma_f32_16x16x32_bf16 v[114:117], v[126:129], v[186:189], v[114:117]
	v_mfma_f32_16x16x32_bf16 v[106:109], v[138:141], v[186:189], v[106:109]
	v_mfma_f32_16x16x32_bf16 v[54:57], v[134:137], v[166:169], v[54:57]
	v_mfma_f32_16x16x32_bf16 v[50:53], v[142:145], v[166:169], v[50:53]
	v_mfma_f32_16x16x32_bf16 v[38:41], v[134:137], v[174:177], v[38:41]
	v_mfma_f32_16x16x32_bf16 v[30:33], v[142:145], v[174:177], v[30:33]
	v_mfma_f32_16x16x32_bf16 v[86:89], v[134:137], v[182:185], v[86:89]
	v_mfma_f32_16x16x32_bf16 v[122:125], v[142:145], v[182:185], v[122:125]
	v_mfma_f32_16x16x32_bf16 v[114:117], v[134:137], v[190:193], v[114:117]
	v_mfma_f32_16x16x32_bf16 v[106:109], v[142:145], v[190:193], v[106:109]
	v_mfma_f32_16x16x32_bf16 v[22:25], v[146:149], v[162:165], v[22:25]
	v_mfma_f32_16x16x32_bf16 v[18:21], v[154:157], v[162:165], v[18:21]
	v_mfma_f32_16x16x32_bf16 v[10:13], v[146:149], v[170:173], v[10:13]
	v_mfma_f32_16x16x32_bf16 v[6:9], v[154:157], v[170:173], v[6:9]
	v_mfma_f32_16x16x32_bf16 v[82:85], v[146:149], v[178:181], v[82:85]
	v_mfma_f32_16x16x32_bf16 v[94:97], v[154:157], v[178:181], v[94:97]
	v_mfma_f32_16x16x32_bf16 v[70:73], v[146:149], v[186:189], v[70:73]
	v_mfma_f32_16x16x32_bf16 v[66:69], v[154:157], v[186:189], v[66:69]
	v_mfma_f32_16x16x32_bf16 v[22:25], v[150:153], v[166:169], v[22:25]
	v_mfma_f32_16x16x32_bf16 v[18:21], v[158:161], v[166:169], v[18:21]
	v_mfma_f32_16x16x32_bf16 v[10:13], v[150:153], v[174:177], v[10:13]
	v_mfma_f32_16x16x32_bf16 v[6:9], v[158:161], v[174:177], v[6:9]
	v_mfma_f32_16x16x32_bf16 v[82:85], v[150:153], v[182:185], v[82:85]
	v_mfma_f32_16x16x32_bf16 v[94:97], v[158:161], v[182:185], v[94:97]
	v_mfma_f32_16x16x32_bf16 v[70:73], v[150:153], v[190:193], v[70:73]
	v_mfma_f32_16x16x32_bf16 v[66:69], v[158:161], v[190:193], v[66:69]
	s_barrier
	s_add_i32 s86, 0, 0x18000
	s_add_i32 s87, 0, 0x1c000
	v_add_u32_e32 v142, s86, v251
	v_add_u32_e32 v158, s87, v251
	ds_read_b128 v[126:129], v142
	ds_read_b128 v[134:137], v142 offset:1024
	ds_read_b128 v[138:141], v142 offset:2048
	ds_read_b128 v[142:145], v142 offset:3072
	ds_read_b128 v[146:149], v158
	ds_read_b128 v[150:153], v158 offset:1024
	ds_read_b128 v[154:157], v158 offset:2048
	ds_read_b128 v[158:161], v158 offset:3072
	s_add_u32 s30, s40, 0x4000
	s_addc_u32 s31, s41, 0
	s_mov_b32 m0, s42
	v_lshl_add_u64 v[202:203], s[30:31], 0, v[236:237]
	ds_read_b128 v[162:165], v252 offset:32768
	ds_read_b128 v[166:169], v252 offset:33792
	ds_read_b128 v[170:173], v252 offset:34816
	ds_read_b128 v[174:177], v252 offset:35840
	ds_read_b128 v[178:181], v252 offset:36864
	ds_read_b128 v[182:185], v252 offset:37888
	ds_read_b128 v[186:189], v252 offset:38912
	ds_read_b128 v[190:193], v252 offset:39936
	global_load_lds_dwordx4 v[202:203], off
	v_lshl_add_u64 v[202:203], s[30:31], 0, v[240:241]
	s_mov_b32 m0, s43
	s_nop 0
	global_load_lds_dwordx4 v[202:203], off
	s_waitcnt vmcnt(8)
	s_waitcnt lgkmcnt(0)
	s_barrier
	s_waitcnt lgkmcnt(0)
	v_mfma_f32_16x16x32_bf16 v[130:133], v[126:129], v[162:165], v[130:133]
	v_mfma_f32_16x16x32_bf16 v[118:121], v[138:141], v[162:165], v[118:121]
	v_mfma_f32_16x16x32_bf16 v[110:113], v[126:129], v[170:173], v[110:113]
	v_mfma_f32_16x16x32_bf16 v[98:101], v[138:141], v[170:173], v[98:101]
	v_mfma_f32_16x16x32_bf16 v[62:65], v[126:129], v[178:181], v[62:65]
	v_mfma_f32_16x16x32_bf16 v[58:61], v[138:141], v[178:181], v[58:61]
	v_mfma_f32_16x16x32_bf16 v[46:49], v[126:129], v[186:189], v[46:49]
	v_mfma_f32_16x16x32_bf16 v[42:45], v[138:141], v[186:189], v[42:45]
	v_mfma_f32_16x16x32_bf16 v[130:133], v[134:137], v[166:169], v[130:133]
	v_mfma_f32_16x16x32_bf16 v[118:121], v[142:145], v[166:169], v[118:121]
	v_mfma_f32_16x16x32_bf16 v[110:113], v[134:137], v[174:177], v[110:113]
	v_mfma_f32_16x16x32_bf16 v[98:101], v[142:145], v[174:177], v[98:101]
	v_mfma_f32_16x16x32_bf16 v[62:65], v[134:137], v[182:185], v[62:65]
	v_mfma_f32_16x16x32_bf16 v[58:61], v[142:145], v[182:185], v[58:61]
	v_mfma_f32_16x16x32_bf16 v[46:49], v[134:137], v[190:193], v[46:49]
	v_mfma_f32_16x16x32_bf16 v[42:45], v[142:145], v[190:193], v[42:45]
	v_mfma_f32_16x16x32_bf16 v[102:105], v[146:149], v[162:165], v[102:105]
	v_mfma_f32_16x16x32_bf16 v[74:77], v[154:157], v[162:165], v[74:77]
	v_mfma_f32_16x16x32_bf16 v[78:81], v[146:149], v[170:173], v[78:81]
	v_mfma_f32_16x16x32_bf16 v[90:93], v[154:157], v[170:173], v[90:93]
	v_mfma_f32_16x16x32_bf16 v[34:37], v[146:149], v[178:181], v[34:37]
	v_mfma_f32_16x16x32_bf16 v[26:29], v[154:157], v[178:181], v[26:29]
	v_mfma_f32_16x16x32_bf16 v[14:17], v[146:149], v[186:189], v[14:17]
	v_mfma_f32_16x16x32_bf16 v[2:5], v[154:157], v[186:189], v[2:5]
	v_mfma_f32_16x16x32_bf16 v[102:105], v[150:153], v[166:169], v[102:105]
	v_mfma_f32_16x16x32_bf16 v[74:77], v[158:161], v[166:169], v[74:77]
	v_mfma_f32_16x16x32_bf16 v[78:81], v[150:153], v[174:177], v[78:81]
	v_mfma_f32_16x16x32_bf16 v[90:93], v[158:161], v[174:177], v[90:93]
	v_mfma_f32_16x16x32_bf16 v[34:37], v[150:153], v[182:185], v[34:37]
	v_mfma_f32_16x16x32_bf16 v[26:29], v[158:161], v[182:185], v[26:29]
	v_mfma_f32_16x16x32_bf16 v[14:17], v[150:153], v[190:193], v[14:17]
	v_mfma_f32_16x16x32_bf16 v[2:5], v[158:161], v[190:193], v[2:5]
	s_barrier
; #define PG8_STAGE(bufoff, gbase, voff) do { _Pragma("unroll") for (int _i = 0; _i < 2; ++_i) \
;         __builtin_amdgcn_global_load_lds((const unsigned*)((const char*)(gbase) + (voff)[_i]), (PG8_LAS unsigned*)(lds + (bufoff) + ldsw + _i * 8192), 16, 0, 0); } while (0)
; #define PG8_LDA(dst, b, h) do { _Pragma("unroll") for (int m = 0; m < 4; ++m) _Pragma("unroll") for (int k = 0; k < 2; ++k) dst[m][k] = *(const PG8_LAS bf16x8*)(lds + PG8_SA(b, h) + aoff + m * 2048 + k * 1024); } while (0)
; #define PG8_MMA(ai, bj, At, Bt) do { __builtin_amdgcn_s_setprio(1); _Pragma("unroll") for (int m = 0; m < 4; ++m) _Pragma("unroll") for (int n = 0; n < 2; ++n) _Pragma("unroll") for (int k = 0; k < 2; ++k) \
;         acc[ai][bj][m][n] = __builtin_amdgcn_mfma_f32_16x16x32_bf16(Bt[n][k], At[m][k], acc[ai][bj][m][n], 0, 0, 0); __builtin_amdgcn_s_setprio(0); } while (0)
; #define PG8_WAIT_V(n) asm volatile("s_waitcnt vmcnt(" #n ")" ::: "memory")
; #define PG8_WAIT_L(n) asm volatile("s_waitcnt lgkmcnt(" #n ")" ::: "memory")
; #define PG8_BAR __builtin_amdgcn_s_barrier()
; #define PG8_SCHED __builtin_amdgcn_sched_barrier(0)
; template <class Epi, class Sched, bool ALIGN_EPI = false, bool SP2 = false>
; __device__ __forceinline__ void gemm_phase(PG8_LAS unsigned char* lds, const Gemm g, const Sched& S, const Epi& E, int wave_s) {
;     ...
;         for (int t = 0; t < nt; t += 2) {
;     ...
;             PG8_LDA(At, 1, 1); PG8_STAGE(PG8_SB(1, 0), b3, voffB); PG8_STAGE(PG8_SB(1, 1), b3 + hstepB, voffB); PG8_STAGE(PG8_SA(1, 0), a3, voffA);
;             PG8_WAIT_V(8); PG8_WAIT_L(0); PG8_BAR; PG8_MMA(1, 0, At, B0); PG8_MMA(1, 1, At, B1); PG8_BAR; PG8_SCHED;
	s_add_i32 s30, s86, s35
	v_lshl_add_u64 v[194:195], v[194:195], 0, s[60:61]
	s_mov_b32 m0, s30
	ds_read_b128 v[162:165], v252 offset:49152
	ds_read_b128 v[166:169], v252 offset:50176
	ds_read_b128 v[170:173], v252 offset:51200
	ds_read_b128 v[174:177], v252 offset:52224
	ds_read_b128 v[178:181], v252 offset:53248
	ds_read_b128 v[182:185], v252 offset:54272
	ds_read_b128 v[186:189], v252 offset:55296
	ds_read_b128 v[190:193], v252 offset:56320
	global_load_lds_dwordx4 v[194:195], off
	s_add_i32 m0, s30, 0x2000
	s_add_u32 s6, s6, 0x80080
	v_lshl_add_u64 v[194:195], v[196:197], 0, s[60:61]
	s_addc_u32 s7, s7, 0
	s_add_i32 s30, s87, s35
	global_load_lds_dwordx4 v[194:195], off
	v_lshl_add_u64 v[194:195], s[6:7], 0, v[238:239]
	s_mov_b32 m0, s30
	s_nop 0
	global_load_lds_dwordx4 v[194:195], off
	v_lshl_add_u64 v[194:195], s[6:7], 0, v[242:243]
	s_add_i32 m0, s30, 0x2000
	s_nop 0
	global_load_lds_dwordx4 v[194:195], off
	v_lshl_add_u64 v[194:195], v[198:199], 0, s[60:61]
	s_mov_b32 m0, s77
	s_nop 0
	global_load_lds_dwordx4 v[194:195], off
	v_lshl_add_u64 v[194:195], v[200:201], 0, s[60:61]
	s_mov_b32 m0, s94
	s_nop 0
	global_load_lds_dwordx4 v[194:195], off
	s_waitcnt vmcnt(8)
	s_waitcnt lgkmcnt(0)
	s_barrier
	s_waitcnt lgkmcnt(0)
	v_mfma_f32_16x16x32_bf16 v[54:57], v[126:129], v[162:165], v[54:57]
	v_mfma_f32_16x16x32_bf16 v[50:53], v[138:141], v[162:165], v[50:53]
	v_mfma_f32_16x16x32_bf16 v[38:41], v[126:129], v[170:173], v[38:41]
	v_mfma_f32_16x16x32_bf16 v[30:33], v[138:141], v[170:173], v[30:33]
	v_mfma_f32_16x16x32_bf16 v[86:89], v[126:129], v[178:181], v[86:89]
	v_mfma_f32_16x16x32_bf16 v[122:125], v[138:141], v[178:181], v[122:125]
	v_mfma_f32_16x16x32_bf16 v[114:117], v[126:129], v[186:189], v[114:117]
	v_mfma_f32_16x16x32_bf16 v[106:109], v[138:141], v[186:189], v[106:109]
	v_mfma_f32_16x16x32_bf16 v[54:57], v[134:137], v[166:169], v[54:57]
	v_mfma_f32_16x16x32_bf16 v[50:53], v[142:145], v[166:169], v[50:53]
	v_mfma_f32_16x16x32_bf16 v[38:41], v[134:137], v[174:177], v[38:41]
	v_mfma_f32_16x16x32_bf16 v[30:33], v[142:145], v[174:177], v[30:33]
	v_mfma_f32_16x16x32_bf16 v[86:89], v[134:137], v[182:185], v[86:89]
	v_mfma_f32_16x16x32_bf16 v[122:125], v[142:145], v[182:185], v[122:125]
	v_mfma_f32_16x16x32_bf16 v[114:117], v[134:137], v[190:193], v[114:117]
	v_mfma_f32_16x16x32_bf16 v[106:109], v[142:145], v[190:193], v[106:109]
	v_mfma_f32_16x16x32_bf16 v[22:25], v[146:149], v[162:165], v[22:25]
	v_mfma_f32_16x16x32_bf16 v[18:21], v[154:157], v[162:165], v[18:21]
	v_mfma_f32_16x16x32_bf16 v[10:13], v[146:149], v[170:173], v[10:13]
	v_mfma_f32_16x16x32_bf16 v[6:9], v[154:157], v[170:173], v[6:9]
	v_mfma_f32_16x16x32_bf16 v[82:85], v[146:149], v[178:181], v[82:85]
	v_mfma_f32_16x16x32_bf16 v[94:97], v[154:157], v[178:181], v[94:97]
	v_mfma_f32_16x16x32_bf16 v[70:73], v[146:149], v[186:189], v[70:73]
	v_mfma_f32_16x16x32_bf16 v[66:69], v[154:157], v[186:189], v[66:69]
	v_mfma_f32_16x16x32_bf16 v[22:25], v[150:153], v[166:169], v[22:25]
	v_mfma_f32_16x16x32_bf16 v[18:21], v[158:161], v[166:169], v[18:21]
	v_mfma_f32_16x16x32_bf16 v[10:13], v[150:153], v[174:177], v[10:13]
	v_mfma_f32_16x16x32_bf16 v[6:9], v[158:161], v[174:177], v[6:9]
	v_mfma_f32_16x16x32_bf16 v[82:85], v[150:153], v[182:185], v[82:85]
	v_mfma_f32_16x16x32_bf16 v[94:97], v[158:161], v[182:185], v[94:97]
	v_mfma_f32_16x16x32_bf16 v[70:73], v[150:153], v[190:193], v[70:73]
	v_mfma_f32_16x16x32_bf16 v[66:69], v[158:161], v[190:193], v[66:69]
	s_barrier
	s_add_i32 vcc_lo, vcc_lo, 2
	s_add_u32 s89, s89, 0x100
	s_addc_u32 s91, s91, 0
	s_cmp_gt_u32 vcc_lo, 29
	s_mov_b64 s[30:31], s[4:5]
	s_cbranch_scc0 .LBB0_691
	s_and_b64 vcc, exec, s[26:27]
	s_cbranch_vccz .LBB0_694
	s_barrier

; #define PG8_STAGE(bufoff, gbase, voff) do { _Pragma("unroll") for (int _i = 0; _i < 2; ++_i) \
;         __builtin_amdgcn_global_load_lds((const unsigned*)((const char*)(gbase) + (voff)[_i]), (PG8_LAS unsigned*)(lds + (bufoff) + ldsw + _i * 8192), 16, 0, 0); } while (0)
; #define PG8_LDA(dst, b, h) do { _Pragma("unroll") for (int m = 0; m < 4; ++m) _Pragma("unroll") for (int k = 0; k < 2; ++k) dst[m][k] = *(const PG8_LAS bf16x8*)(lds + PG8_SA(b, h) + aoff + m * 2048 + k * 1024); } while (0)
; #define PG8_LDB(dst, b, h) do { _Pragma("unroll") for (int n = 0; n < 2; ++n) _Pragma("unroll") for (int k = 0; k < 2; ++k) dst[n][k] = *(const PG8_LAS bf16x8*)(lds + PG8_SB(b, h) + boff + n * 2048 + k * 1024); } while (0)
; #define PG8_MMA(ai, bj, At, Bt) do { __builtin_amdgcn_s_setprio(1); _Pragma("unroll") for (int m = 0; m < 4; ++m) _Pragma("unroll") for (int n = 0; n < 2; ++n) _Pragma("unroll") for (int k = 0; k < 2; ++k) \
;         acc[ai][bj][m][n] = __builtin_amdgcn_mfma_f32_16x16x32_bf16(Bt[n][k], At[m][k], acc[ai][bj][m][n], 0, 0, 0); __builtin_amdgcn_s_setprio(0); } while (0)
; #define PG8_WAIT_V(n) asm volatile("s_waitcnt vmcnt(" #n ")" ::: "memory")
; #define PG8_WAIT_L(n) asm volatile("s_waitcnt lgkmcnt(" #n ")" ::: "memory")
; #define PG8_BAR __builtin_amdgcn_s_barrier()
; #define PG8_SCHED __builtin_amdgcn_sched_barrier(0)
; template <class Epi, class Sched, bool ALIGN_EPI = false, bool SP2 = false>
; __device__ __forceinline__ void gemm_phase(PG8_LAS unsigned char* lds, const Gemm g, const Sched& S, const Epi& E, int wave_s) {
;     ...
;             const bool last = (t == nt - 2);
;             const char* a1 = cA + (size_t)(t + 1) * kstep;
;             const char* a2 = last ? nA : cA + (size_t)(t + 2) * kstep; const char* b2 = last ? nB : cB + (size_t)(t + 2) * kstep;
;             const char* a3 = a2 + kstep; const char* b3 = b2 + kstep;
;             if (last && has_next) S.a_ready(nxt);
;             if constexpr (SP2) {
;             PG8_LDB(B0, 0, 0); PG8_LDB(B1, 0, 1); PG8_SCHED; PG8_LDA(At, 0, 0); PG8_STAGE(PG8_SA(1, 1), a1 + hstepA, voffA);
;             PG8_WAIT_V(8); PG8_WAIT_L(0); PG8_BAR; PG8_MMA(0, 0, At, B0); PG8_MMA(0, 1, At, B1); PG8_BAR; PG8_SCHED;
;             PG8_LDA(At, 0, 1); PG8_STAGE(PG8_SB(0, 0), b2, voffB); PG8_STAGE(PG8_SB(0, 1), b2 + hstepB, voffB); PG8_STAGE(PG8_SA(0, 0), a2, voffA);
.LBB0_786:
	s_add_i32 s84, 0, 0x10000
	s_add_i32 s85, 0, 0x14000
	v_add_u32_e32 v110, s84, v211
	v_add_u32_e32 v150, s85, v211
	ds_read_b128 v[78:81], v110
	ds_read_b128 v[86:89], v110 offset:1024
	ds_read_b128 v[102:105], v110 offset:2048
	ds_read_b128 v[110:113], v110 offset:3072
	ds_read_b128 v[122:125], v150
	ds_read_b128 v[134:137], v150 offset:1024
	ds_read_b128 v[146:149], v150 offset:2048
	ds_read_b128 v[150:153], v150 offset:3072
	s_add_u32 s4, s8, 0x100
	s_addc_u32 s5, s9, 0
	s_cmpk_eq_i32 s81, 0x54
	s_cselect_b32 s31, s95, s5
	s_cselect_b32 s30, s94, s4
	s_cselect_b32 s7, s97, s3
	s_cselect_b32 s6, s96, s2
	v_lshl_add_u64 v[206:207], s[8:9], 0, v[198:199]
	s_add_i32 m0, s35, 0xc000
	ds_read_b128 v[162:165], v212
	ds_read_b128 v[166:169], v212 offset:1024
	ds_read_b128 v[170:173], v212 offset:2048
	ds_read_b128 v[174:177], v212 offset:3072
	ds_read_b128 v[178:181], v212 offset:4096
	ds_read_b128 v[182:185], v212 offset:5120
	ds_read_b128 v[186:189], v212 offset:6144
	ds_read_b128 v[202:205], v212 offset:7168
	global_load_lds_dwordx4 v[206:207], off
	v_lshl_add_u64 v[206:207], s[8:9], 0, v[200:201]
	s_add_i32 m0, s35, 0xe000
	s_nop 0
	global_load_lds_dwordx4 v[206:207], off
	s_waitcnt vmcnt(8)
	s_waitcnt lgkmcnt(0)
	s_barrier
	s_waitcnt lgkmcnt(0)
	v_mfma_f32_16x16x32_bf16 v[158:161], v[78:81], v[162:165], v[158:161]
	v_mfma_f32_16x16x32_bf16 v[154:157], v[102:105], v[162:165], v[154:157]
	v_mfma_f32_16x16x32_bf16 v[130:133], v[78:81], v[170:173], v[130:133]
	v_mfma_f32_16x16x32_bf16 v[126:129], v[102:105], v[170:173], v[126:129]
	v_mfma_f32_16x16x32_bf16 v[106:109], v[78:81], v[178:181], v[106:109]
	v_mfma_f32_16x16x32_bf16 v[98:101], v[102:105], v[178:181], v[98:101]
	v_mfma_f32_16x16x32_bf16 v[82:85], v[78:81], v[186:189], v[82:85]
	v_mfma_f32_16x16x32_bf16 v[74:77], v[102:105], v[186:189], v[74:77]
	v_mfma_f32_16x16x32_bf16 v[158:161], v[86:89], v[166:169], v[158:161]
	v_mfma_f32_16x16x32_bf16 v[154:157], v[110:113], v[166:169], v[154:157]
	v_mfma_f32_16x16x32_bf16 v[130:133], v[86:89], v[174:177], v[130:133]
	v_mfma_f32_16x16x32_bf16 v[126:129], v[110:113], v[174:177], v[126:129]
	v_mfma_f32_16x16x32_bf16 v[106:109], v[86:89], v[182:185], v[106:109]
	v_mfma_f32_16x16x32_bf16 v[98:101], v[110:113], v[182:185], v[98:101]
	v_mfma_f32_16x16x32_bf16 v[82:85], v[86:89], v[202:205], v[82:85]
	v_mfma_f32_16x16x32_bf16 v[74:77], v[110:113], v[202:205], v[74:77]
	v_mfma_f32_16x16x32_bf16 v[142:145], v[122:125], v[162:165], v[142:145]
	v_mfma_f32_16x16x32_bf16 v[138:141], v[146:149], v[162:165], v[138:141]
	v_mfma_f32_16x16x32_bf16 v[118:121], v[122:125], v[170:173], v[118:121]
	v_mfma_f32_16x16x32_bf16 v[114:117], v[146:149], v[170:173], v[114:117]
	v_mfma_f32_16x16x32_bf16 v[94:97], v[122:125], v[178:181], v[94:97]
	v_mfma_f32_16x16x32_bf16 v[90:93], v[146:149], v[178:181], v[90:93]
	v_mfma_f32_16x16x32_bf16 v[70:73], v[122:125], v[186:189], v[70:73]
	v_mfma_f32_16x16x32_bf16 v[66:69], v[146:149], v[186:189], v[66:69]
	v_mfma_f32_16x16x32_bf16 v[142:145], v[134:137], v[166:169], v[142:145]
	v_mfma_f32_16x16x32_bf16 v[138:141], v[150:153], v[166:169], v[138:141]
	v_mfma_f32_16x16x32_bf16 v[118:121], v[134:137], v[174:177], v[118:121]
	v_mfma_f32_16x16x32_bf16 v[114:117], v[150:153], v[174:177], v[114:117]
	v_mfma_f32_16x16x32_bf16 v[94:97], v[134:137], v[182:185], v[94:97]
	v_mfma_f32_16x16x32_bf16 v[90:93], v[150:153], v[182:185], v[90:93]
	v_mfma_f32_16x16x32_bf16 v[70:73], v[134:137], v[202:205], v[70:73]
	v_mfma_f32_16x16x32_bf16 v[66:69], v[150:153], v[202:205], v[66:69]
	s_barrier
	s_add_i32 s8, s84, s22
	v_lshl_add_u64 v[206:207], s[6:7], 0, v[194:195]
	s_mov_b32 m0, s8
	ds_read_b128 v[162:165], v212 offset:16384
	ds_read_b128 v[166:169], v212 offset:17408
	ds_read_b128 v[170:173], v212 offset:18432
	ds_read_b128 v[174:177], v212 offset:19456
	ds_read_b128 v[178:181], v212 offset:20480
	ds_read_b128 v[182:185], v212 offset:21504
	ds_read_b128 v[186:189], v212 offset:22528
	ds_read_b128 v[202:205], v212 offset:23552
	global_load_lds_dwordx4 v[206:207], off
	s_add_i32 m0, s8, 0x2000
	s_add_u32 s8, s6, 0x160000
	v_lshl_add_u64 v[208:209], s[6:7], 0, v[190:191]
	s_addc_u32 s9, s7, 0
	s_add_i32 s84, s85, s22
	global_load_lds_dwordx4 v[208:209], off
	v_lshl_add_u64 v[214:215], s[8:9], 0, v[194:195]
	s_mov_b32 m0, s84
	v_lshl_add_u64 v[216:217], s[30:31], 0, v[192:193]
	global_load_lds_dwordx4 v[214:215], off
	v_lshl_add_u64 v[214:215], s[8:9], 0, v[190:191]
	s_add_i32 m0, s84, 0x2000
	s_nop 0
	global_load_lds_dwordx4 v[214:215], off
	v_lshl_add_u64 v[214:215], s[30:31], 0, v[196:197]
	s_mov_b32 m0, s35
	s_nop 0
	global_load_lds_dwordx4 v[214:215], off
	s_mov_b32 m0, s36
	s_nop 0
	global_load_lds_dwordx4 v[216:217], off
	s_waitcnt vmcnt(8)
	s_waitcnt lgkmcnt(0)
	s_barrier
; #define PG8_STAGE(bufoff, gbase, voff) do { _Pragma("unroll") for (int _i = 0; _i < 2; ++_i) \
;         __builtin_amdgcn_global_load_lds((const unsigned*)((const char*)(gbase) + (voff)[_i]), (PG8_LAS unsigned*)(lds + (bufoff) + ldsw + _i * 8192), 16, 0, 0); } while (0)
; #define PG8_LDA(dst, b, h) do { _Pragma("unroll") for (int m = 0; m < 4; ++m) _Pragma("unroll") for (int k = 0; k < 2; ++k) dst[m][k] = *(const PG8_LAS bf16x8*)(lds + PG8_SA(b, h) + aoff + m * 2048 + k * 1024); } while (0)
; #define PG8_LDB(dst, b, h) do { _Pragma("unroll") for (int n = 0; n < 2; ++n) _Pragma("unroll") for (int k = 0; k < 2; ++k) dst[n][k] = *(const PG8_LAS bf16x8*)(lds + PG8_SB(b, h) + boff + n * 2048 + k * 1024); } while (0)
; #define PG8_MMA(ai, bj, At, Bt) do { __builtin_amdgcn_s_setprio(1); _Pragma("unroll") for (int m = 0; m < 4; ++m) _Pragma("unroll") for (int n = 0; n < 2; ++n) _Pragma("unroll") for (int k = 0; k < 2; ++k) \
;         acc[ai][bj][m][n] = __builtin_amdgcn_mfma_f32_16x16x32_bf16(Bt[n][k], At[m][k], acc[ai][bj][m][n], 0, 0, 0); __builtin_amdgcn_s_setprio(0); } while (0)
; #define PG8_WAIT_V(n) asm volatile("s_waitcnt vmcnt(" #n ")" ::: "memory")
; #define PG8_WAIT_L(n) asm volatile("s_waitcnt lgkmcnt(" #n ")" ::: "memory")
; #define PG8_BAR __builtin_amdgcn_s_barrier()
; #define PG8_SCHED __builtin_amdgcn_sched_barrier(0)
; template <class Epi, class Sched, bool ALIGN_EPI = false, bool SP2 = false>
; __device__ __forceinline__ void gemm_phase(PG8_LAS unsigned char* lds, const Gemm g, const Sched& S, const Epi& E, int wave_s) {
;     ...
;             PG8_WAIT_V(8); PG8_WAIT_L(0); PG8_BAR; PG8_MMA(1, 0, At, B0); PG8_MMA(1, 1, At, B1); PG8_BAR; PG8_SCHED;
;             PG8_LDB(B0, 1, 0); PG8_LDB(B1, 1, 1); PG8_SCHED; PG8_LDA(At, 1, 0); PG8_STAGE(PG8_SA(0, 1), a2 + hstepA, voffA);
;             PG8_WAIT_V(8); PG8_WAIT_L(0); PG8_BAR; PG8_MMA(0, 0, At, B0); PG8_MMA(0, 1, At, B1); PG8_BAR; PG8_SCHED;
	s_waitcnt lgkmcnt(0)
	v_mfma_f32_16x16x32_bf16 v[62:65], v[78:81], v[162:165], v[62:65]
	v_mfma_f32_16x16x32_bf16 v[58:61], v[102:105], v[162:165], v[58:61]
	v_mfma_f32_16x16x32_bf16 v[46:49], v[78:81], v[170:173], v[46:49]
	v_mfma_f32_16x16x32_bf16 v[42:45], v[102:105], v[170:173], v[42:45]
	v_mfma_f32_16x16x32_bf16 v[30:33], v[78:81], v[178:181], v[30:33]
	v_mfma_f32_16x16x32_bf16 v[26:29], v[102:105], v[178:181], v[26:29]
	v_mfma_f32_16x16x32_bf16 v[14:17], v[78:81], v[186:189], v[14:17]
	v_mfma_f32_16x16x32_bf16 v[10:13], v[102:105], v[186:189], v[10:13]
	v_mfma_f32_16x16x32_bf16 v[62:65], v[86:89], v[166:169], v[62:65]
	v_mfma_f32_16x16x32_bf16 v[58:61], v[110:113], v[166:169], v[58:61]
	v_mfma_f32_16x16x32_bf16 v[46:49], v[86:89], v[174:177], v[46:49]
	v_mfma_f32_16x16x32_bf16 v[42:45], v[110:113], v[174:177], v[42:45]
	v_mfma_f32_16x16x32_bf16 v[30:33], v[86:89], v[182:185], v[30:33]
	v_mfma_f32_16x16x32_bf16 v[26:29], v[110:113], v[182:185], v[26:29]
	v_mfma_f32_16x16x32_bf16 v[14:17], v[86:89], v[202:205], v[14:17]
	v_mfma_f32_16x16x32_bf16 v[10:13], v[110:113], v[202:205], v[10:13]
	v_mfma_f32_16x16x32_bf16 v[54:57], v[122:125], v[162:165], v[54:57]
	v_mfma_f32_16x16x32_bf16 v[50:53], v[146:149], v[162:165], v[50:53]
	v_mfma_f32_16x16x32_bf16 v[38:41], v[122:125], v[170:173], v[38:41]
	v_mfma_f32_16x16x32_bf16 v[34:37], v[146:149], v[170:173], v[34:37]
	v_mfma_f32_16x16x32_bf16 v[22:25], v[122:125], v[178:181], v[22:25]
	v_mfma_f32_16x16x32_bf16 v[18:21], v[146:149], v[178:181], v[18:21]
	v_mfma_f32_16x16x32_bf16 v[6:9], v[122:125], v[186:189], v[6:9]
	v_mfma_f32_16x16x32_bf16 v[2:5], v[146:149], v[186:189], v[2:5]
	v_mfma_f32_16x16x32_bf16 v[54:57], v[134:137], v[166:169], v[54:57]
	v_mfma_f32_16x16x32_bf16 v[50:53], v[150:153], v[166:169], v[50:53]
	v_mfma_f32_16x16x32_bf16 v[38:41], v[134:137], v[174:177], v[38:41]
	v_mfma_f32_16x16x32_bf16 v[34:37], v[150:153], v[174:177], v[34:37]
	v_mfma_f32_16x16x32_bf16 v[22:25], v[134:137], v[182:185], v[22:25]
	v_mfma_f32_16x16x32_bf16 v[18:21], v[150:153], v[182:185], v[18:21]
	v_mfma_f32_16x16x32_bf16 v[6:9], v[134:137], v[202:205], v[6:9]
	v_mfma_f32_16x16x32_bf16 v[2:5], v[150:153], v[202:205], v[2:5]
	s_barrier
	s_add_i32 s84, 0, 0x18000
	s_add_i32 s85, 0, 0x1c000
	v_add_u32_e32 v110, s84, v211
	v_add_u32_e32 v150, s85, v211
	ds_read_b128 v[78:81], v110
	ds_read_b128 v[86:89], v110 offset:1024
	ds_read_b128 v[102:105], v110 offset:2048
	ds_read_b128 v[110:113], v110 offset:3072
	ds_read_b128 v[122:125], v150
	ds_read_b128 v[134:137], v150 offset:1024
	ds_read_b128 v[146:149], v150 offset:2048
	ds_read_b128 v[150:153], v150 offset:3072
	s_add_u32 s8, s30, 0x160000
	s_addc_u32 s9, s31, 0
	s_mov_b32 m0, s37
	v_lshl_add_u64 v[218:219], s[8:9], 0, v[196:197]
	ds_read_b128 v[162:165], v212 offset:32768
	ds_read_b128 v[166:169], v212 offset:33792
	ds_read_b128 v[170:173], v212 offset:34816
	ds_read_b128 v[174:177], v212 offset:35840
	ds_read_b128 v[178:181], v212 offset:36864
	ds_read_b128 v[182:185], v212 offset:37888
	ds_read_b128 v[186:189], v212 offset:38912
	ds_read_b128 v[202:205], v212 offset:39936
	global_load_lds_dwordx4 v[218:219], off
	v_lshl_add_u64 v[218:219], s[8:9], 0, v[192:193]
	s_mov_b32 m0, s40
	s_nop 0
	global_load_lds_dwordx4 v[218:219], off
	s_waitcnt vmcnt(8)
	s_waitcnt lgkmcnt(0)
	s_barrier
	s_waitcnt lgkmcnt(0)
	v_mfma_f32_16x16x32_bf16 v[158:161], v[78:81], v[162:165], v[158:161]
	v_mfma_f32_16x16x32_bf16 v[154:157], v[102:105], v[162:165], v[154:157]
	v_mfma_f32_16x16x32_bf16 v[130:133], v[78:81], v[170:173], v[130:133]
	v_mfma_f32_16x16x32_bf16 v[126:129], v[102:105], v[170:173], v[126:129]
	v_mfma_f32_16x16x32_bf16 v[106:109], v[78:81], v[178:181], v[106:109]
	v_mfma_f32_16x16x32_bf16 v[98:101], v[102:105], v[178:181], v[98:101]
	v_mfma_f32_16x16x32_bf16 v[82:85], v[78:81], v[186:189], v[82:85]
	v_mfma_f32_16x16x32_bf16 v[74:77], v[102:105], v[186:189], v[74:77]
	v_mfma_f32_16x16x32_bf16 v[158:161], v[86:89], v[166:169], v[158:161]
	v_mfma_f32_16x16x32_bf16 v[154:157], v[110:113], v[166:169], v[154:157]
	v_mfma_f32_16x16x32_bf16 v[130:133], v[86:89], v[174:177], v[130:133]
	v_mfma_f32_16x16x32_bf16 v[126:129], v[110:113], v[174:177], v[126:129]
	v_mfma_f32_16x16x32_bf16 v[106:109], v[86:89], v[182:185], v[106:109]
	v_mfma_f32_16x16x32_bf16 v[98:101], v[110:113], v[182:185], v[98:101]
	v_mfma_f32_16x16x32_bf16 v[82:85], v[86:89], v[202:205], v[82:85]
	v_mfma_f32_16x16x32_bf16 v[74:77], v[110:113], v[202:205], v[74:77]
	v_mfma_f32_16x16x32_bf16 v[142:145], v[122:125], v[162:165], v[142:145]
	v_mfma_f32_16x16x32_bf16 v[138:141], v[146:149], v[162:165], v[138:141]
	v_mfma_f32_16x16x32_bf16 v[118:121], v[122:125], v[170:173], v[118:121]
	v_mfma_f32_16x16x32_bf16 v[114:117], v[146:149], v[170:173], v[114:117]
	v_mfma_f32_16x16x32_bf16 v[94:97], v[122:125], v[178:181], v[94:97]
	v_mfma_f32_16x16x32_bf16 v[90:93], v[146:149], v[178:181], v[90:93]
	v_mfma_f32_16x16x32_bf16 v[70:73], v[122:125], v[186:189], v[70:73]
	v_mfma_f32_16x16x32_bf16 v[66:69], v[146:149], v[186:189], v[66:69]
	v_mfma_f32_16x16x32_bf16 v[142:145], v[134:137], v[166:169], v[142:145]
	v_mfma_f32_16x16x32_bf16 v[138:141], v[150:153], v[166:169], v[138:141]
	v_mfma_f32_16x16x32_bf16 v[118:121], v[134:137], v[174:177], v[118:121]
	v_mfma_f32_16x16x32_bf16 v[114:117], v[150:153], v[174:177], v[114:117]
	v_mfma_f32_16x16x32_bf16 v[94:97], v[134:137], v[182:185], v[94:97]
	v_mfma_f32_16x16x32_bf16 v[90:93], v[150:153], v[182:185], v[90:93]
	v_mfma_f32_16x16x32_bf16 v[70:73], v[134:137], v[202:205], v[70:73]
	v_mfma_f32_16x16x32_bf16 v[66:69], v[150:153], v[202:205], v[66:69]
	s_barrier
; #define PG8_STAGE(bufoff, gbase, voff) do { _Pragma("unroll") for (int _i = 0; _i < 2; ++_i) \
;         __builtin_amdgcn_global_load_lds((const unsigned*)((const char*)(gbase) + (voff)[_i]), (PG8_LAS unsigned*)(lds + (bufoff) + ldsw + _i * 8192), 16, 0, 0); } while (0)
; #define PG8_LDA(dst, b, h) do { _Pragma("unroll") for (int m = 0; m < 4; ++m) _Pragma("unroll") for (int k = 0; k < 2; ++k) dst[m][k] = *(const PG8_LAS bf16x8*)(lds + PG8_SA(b, h) + aoff + m * 2048 + k * 1024); } while (0)
; #define PG8_MMA(ai, bj, At, Bt) do { __builtin_amdgcn_s_setprio(1); _Pragma("unroll") for (int m = 0; m < 4; ++m) _Pragma("unroll") for (int n = 0; n < 2; ++n) _Pragma("unroll") for (int k = 0; k < 2; ++k) \
;         acc[ai][bj][m][n] = __builtin_amdgcn_mfma_f32_16x16x32_bf16(Bt[n][k], At[m][k], acc[ai][bj][m][n], 0, 0, 0); __builtin_amdgcn_s_setprio(0); } while (0)
; #define PG8_WAIT_V(n) asm volatile("s_waitcnt vmcnt(" #n ")" ::: "memory")
; #define PG8_WAIT_L(n) asm volatile("s_waitcnt lgkmcnt(" #n ")" ::: "memory")
; #define PG8_BAR __builtin_amdgcn_s_barrier()
; #define PG8_SCHED __builtin_amdgcn_sched_barrier(0)
; template <class Epi, class Sched, bool ALIGN_EPI = false, bool SP2 = false>
; __device__ __forceinline__ void gemm_phase(PG8_LAS unsigned char* lds, const Gemm g, const Sched& S, const Epi& E, int wave_s) {
;     ...
;         for (int t = 0; t < nt; t += 2) {
;     ...
;             PG8_LDA(At, 1, 1); PG8_STAGE(PG8_SB(1, 0), b3, voffB); PG8_STAGE(PG8_SB(1, 1), b3 + hstepB, voffB); PG8_STAGE(PG8_SA(1, 0), a3, voffA);
;             PG8_WAIT_V(8); PG8_WAIT_L(0); PG8_BAR; PG8_MMA(1, 0, At, B0); PG8_MMA(1, 1, At, B1); PG8_BAR; PG8_SCHED;
	s_add_i32 s8, s84, s22
	v_lshl_add_u64 v[206:207], v[206:207], 0, s[60:61]
	s_mov_b32 m0, s8
	ds_read_b128 v[162:165], v212 offset:49152
	ds_read_b128 v[166:169], v212 offset:50176
	ds_read_b128 v[170:173], v212 offset:51200
	ds_read_b128 v[174:177], v212 offset:52224
	ds_read_b128 v[178:181], v212 offset:53248
	ds_read_b128 v[182:185], v212 offset:54272
	ds_read_b128 v[186:189], v212 offset:55296
	ds_read_b128 v[202:205], v212 offset:56320
	global_load_lds_dwordx4 v[206:207], off
	s_add_i32 m0, s8, 0x2000
	s_add_u32 s6, s6, 0x160080
	v_lshl_add_u64 v[206:207], v[208:209], 0, s[60:61]
	s_addc_u32 s7, s7, 0
	s_add_i32 s8, s85, s22
	global_load_lds_dwordx4 v[206:207], off
	v_lshl_add_u64 v[206:207], s[6:7], 0, v[194:195]
	s_mov_b32 m0, s8
	s_nop 0
	global_load_lds_dwordx4 v[206:207], off
	v_lshl_add_u64 v[206:207], s[6:7], 0, v[190:191]
	s_add_i32 m0, s8, 0x2000
	s_nop 0
	global_load_lds_dwordx4 v[206:207], off
	v_lshl_add_u64 v[206:207], v[214:215], 0, s[60:61]
	s_mov_b32 m0, s44
	s_nop 0
	global_load_lds_dwordx4 v[206:207], off
	v_lshl_add_u64 v[206:207], v[216:217], 0, s[60:61]
	s_mov_b32 m0, s45
	s_nop 0
	global_load_lds_dwordx4 v[206:207], off
	s_waitcnt vmcnt(8)
	s_waitcnt lgkmcnt(0)
	s_barrier
	s_waitcnt lgkmcnt(0)
	v_mfma_f32_16x16x32_bf16 v[62:65], v[78:81], v[162:165], v[62:65]
	v_mfma_f32_16x16x32_bf16 v[58:61], v[102:105], v[162:165], v[58:61]
	v_mfma_f32_16x16x32_bf16 v[46:49], v[78:81], v[170:173], v[46:49]
	v_mfma_f32_16x16x32_bf16 v[42:45], v[102:105], v[170:173], v[42:45]
	v_mfma_f32_16x16x32_bf16 v[30:33], v[78:81], v[178:181], v[30:33]
	v_mfma_f32_16x16x32_bf16 v[26:29], v[102:105], v[178:181], v[26:29]
	v_mfma_f32_16x16x32_bf16 v[14:17], v[78:81], v[186:189], v[14:17]
	v_mfma_f32_16x16x32_bf16 v[10:13], v[102:105], v[186:189], v[10:13]
	v_mfma_f32_16x16x32_bf16 v[62:65], v[86:89], v[166:169], v[62:65]
	v_mfma_f32_16x16x32_bf16 v[58:61], v[110:113], v[166:169], v[58:61]
	v_mfma_f32_16x16x32_bf16 v[46:49], v[86:89], v[174:177], v[46:49]
	v_mfma_f32_16x16x32_bf16 v[42:45], v[110:113], v[174:177], v[42:45]
	v_mfma_f32_16x16x32_bf16 v[30:33], v[86:89], v[182:185], v[30:33]
	v_mfma_f32_16x16x32_bf16 v[26:29], v[110:113], v[182:185], v[26:29]
	v_mfma_f32_16x16x32_bf16 v[14:17], v[86:89], v[202:205], v[14:17]
	v_mfma_f32_16x16x32_bf16 v[10:13], v[110:113], v[202:205], v[10:13]
	v_mfma_f32_16x16x32_bf16 v[54:57], v[122:125], v[162:165], v[54:57]
	v_mfma_f32_16x16x32_bf16 v[50:53], v[146:149], v[162:165], v[50:53]
	v_mfma_f32_16x16x32_bf16 v[38:41], v[122:125], v[170:173], v[38:41]
	v_mfma_f32_16x16x32_bf16 v[34:37], v[146:149], v[170:173], v[34:37]
	v_mfma_f32_16x16x32_bf16 v[22:25], v[122:125], v[178:181], v[22:25]
	v_mfma_f32_16x16x32_bf16 v[18:21], v[146:149], v[178:181], v[18:21]
	v_mfma_f32_16x16x32_bf16 v[6:9], v[122:125], v[186:189], v[6:9]
	v_mfma_f32_16x16x32_bf16 v[2:5], v[146:149], v[186:189], v[2:5]
	v_mfma_f32_16x16x32_bf16 v[54:57], v[134:137], v[166:169], v[54:57]
	v_mfma_f32_16x16x32_bf16 v[50:53], v[150:153], v[166:169], v[50:53]
	v_mfma_f32_16x16x32_bf16 v[38:41], v[134:137], v[174:177], v[38:41]
	v_mfma_f32_16x16x32_bf16 v[34:37], v[150:153], v[174:177], v[34:37]
	v_mfma_f32_16x16x32_bf16 v[22:25], v[134:137], v[182:185], v[22:25]
	v_mfma_f32_16x16x32_bf16 v[18:21], v[150:153], v[182:185], v[18:21]
	v_mfma_f32_16x16x32_bf16 v[6:9], v[134:137], v[202:205], v[6:9]
	v_mfma_f32_16x16x32_bf16 v[2:5], v[150:153], v[202:205], v[2:5]
	s_barrier
	s_add_i32 s81, s81, 2
	s_add_u32 s2, s2, 0x100
	s_addc_u32 s3, s3, 0
	s_cmpk_gt_u32 s81, 0x55
	s_mov_b64 s[8:9], s[4:5]
	s_cbranch_scc0 .LBB0_786
	s_and_b64 vcc, exec, s[88:89]
	s_cbranch_vccz .LBB0_789
	s_barrier
